# relax vmcnt(0)->vmcnt(6) at top of EpiStore/EpiFF GEMM epilogues (row scales were loaded before the K-loop; in-order retire)
# speedup vs baseline: 1.0304x; 1.0304x over previous
; #define PG8_STAGE(bufoff, gbase, voff) do { _Pragma("unroll") for (int _i = 0; _i < 2; ++_i) \
;         __builtin_amdgcn_global_load_lds((const unsigned*)((const char*)(gbase) + (voff)[_i]), (LAS unsigned*)(lds + (bufoff) + ldsw + _i * 8192), 16, 0, 0); } while (0)
; #define PG8_LDA(dst, b, h) do { _Pragma("unroll") for (int m = 0; m < 4; ++m) _Pragma("unroll") for (int k = 0; k < 2; ++k) dst[m][k] = *(const LAS bf16x8*)(lds + PG8_SA(b, h) + aoff + m * 2048 + k * 1024); } while (0)
; #define PG8_LDB(dst, b, h) do { _Pragma("unroll") for (int n = 0; n < 2; ++n) _Pragma("unroll") for (int k = 0; k < 2; ++k) dst[n][k] = *(const LAS bf16x8*)(lds + PG8_SB(b, h) + boff + n * 2048 + k * 1024); } while (0)
; #define PG8_MMA(ai, bj, At, Bt) do { __builtin_amdgcn_s_setprio(1); _Pragma("unroll") for (int m = 0; m < 4; ++m) _Pragma("unroll") for (int n = 0; n < 2; ++n) _Pragma("unroll") for (int k = 0; k < 2; ++k) \
;         acc[ai][bj][m][n] = __builtin_amdgcn_mfma_f32_16x16x32_bf16(Bt[n][k], At[m][k], acc[ai][bj][m][n], 0, 0, 0); __builtin_amdgcn_s_setprio(0); } while (0)
; #define PG8_WAIT_V(n) asm volatile("s_waitcnt vmcnt(" #n ")" ::: "memory")
; #define PG8_WAIT_L(n) asm volatile("s_waitcnt lgkmcnt(" #n ")" ::: "memory")
; #define PG8_BAR __builtin_amdgcn_s_barrier()
; #define PG8_SCHED __builtin_amdgcn_sched_barrier(0)
; template <class Epi>
; __device__ __forceinline__ void gemm_phase(LAS unsigned char* lds, const Gemm g, const StaticOrder& S, const Epi& E) {
;     ...
;             const char* a1 = cA + (size_t)(t + 1) * kstep;
;             const char* a2 = last ? nA : cA + (size_t)(t + 2) * kstep; const char* b2 = last ? nB : cB + (size_t)(t + 2) * kstep;
;             const char* a3 = a2 + kstep; const char* b3 = b2 + kstep;
;             PG8_LDB(B0, 0, 0); PG8_SCHED; PG8_LDA(At, 0, 0); PG8_STAGE(PG8_SA(1, 1), a1 + hA, voffA);
;             PG8_WAIT_L(8); PG8_BAR; PG8_WAIT_L(0); PG8_MMA(0, 0, At, B0); PG8_BAR; PG8_SCHED;
;             PG8_LDB(B1, 0, 1); PG8_STAGE(PG8_SB(0, 0), b2, voffB);
;             PG8_BAR; PG8_WAIT_L(0); PG8_MMA(0, 1, At, B1); PG8_BAR;
;             PG8_LDA(At, 0, 1); PG8_STAGE(PG8_SA(0, 0), a2, voffA);
;             PG8_BAR; PG8_WAIT_L(0); PG8_MMA(1, 0, At, B0); PG8_BAR; PG8_SCHED;
;             PG8_STAGE(PG8_SB(0, 1), b2 + hB, voffB);
;             PG8_WAIT_V(6); PG8_BAR; PG8_MMA(1, 1, At, B1); PG8_BAR;
.LBB0_104:
	s_add_u32 s22, s62, 0xfffc0080
	s_addc_u32 s23, s63, -1
	s_add_i32 s75, 0, 0x10000
	v_add_u32_e32 v151, s75, v147
	ds_read_b128 v[156:159], v151
	ds_read_b128 v[160:163], v151 offset:1024
	ds_read_b128 v[164:167], v151 offset:2048
	ds_read_b128 v[168:171], v151 offset:3072
	s_cmp_eq_u32 s74, 12
	s_cselect_b32 s67, s43, s23
	s_cselect_b32 s66, s61, s22
	s_cselect_b32 s65, s41, s71
	s_cselect_b32 s64, s69, s70
	v_lshl_add_u64 v[210:211], s[62:63], 0, v[138:139]
	s_add_i32 m0, s50, 0xc000
	ds_read_b128 v[172:175], v149
	ds_read_b128 v[176:179], v149 offset:1024
	ds_read_b128 v[180:183], v149 offset:2048
	ds_read_b128 v[184:187], v149 offset:3072
	ds_read_b128 v[188:191], v149 offset:4096
	ds_read_b128 v[192:195], v149 offset:5120
	ds_read_b128 v[202:205], v149 offset:6144
	ds_read_b128 v[206:209], v149 offset:7168
	global_load_lds_dwordx4 v[210:211], off
	v_lshl_add_u64 v[210:211], s[62:63], 0, v[140:141]
	s_add_i32 m0, s50, 0xe000
	s_nop 0
	global_load_lds_dwordx4 v[210:211], off
	s_waitcnt lgkmcnt(8)
	s_barrier
	s_waitcnt lgkmcnt(0)
	s_setprio 1
	s_waitcnt lgkmcnt(0)
	v_mfma_f32_16x16x32_bf16 v[126:129], v[156:159], v[172:175], v[126:129]
	v_mfma_f32_16x16x32_bf16 v[118:121], v[164:167], v[172:175], v[118:121]
	v_mfma_f32_16x16x32_bf16 v[110:113], v[156:159], v[180:183], v[110:113]
	v_mfma_f32_16x16x32_bf16 v[102:105], v[164:167], v[180:183], v[102:105]
	v_mfma_f32_16x16x32_bf16 v[94:97], v[156:159], v[188:191], v[94:97]
	v_mfma_f32_16x16x32_bf16 v[86:89], v[164:167], v[188:191], v[86:89]
	v_mfma_f32_16x16x32_bf16 v[78:81], v[156:159], v[202:205], v[78:81]
	v_mfma_f32_16x16x32_bf16 v[70:73], v[164:167], v[202:205], v[70:73]
	v_mfma_f32_16x16x32_bf16 v[126:129], v[160:163], v[176:179], v[126:129]
	v_mfma_f32_16x16x32_bf16 v[118:121], v[168:171], v[176:179], v[118:121]
	v_mfma_f32_16x16x32_bf16 v[110:113], v[160:163], v[184:187], v[110:113]
	v_mfma_f32_16x16x32_bf16 v[102:105], v[168:171], v[184:187], v[102:105]
	v_mfma_f32_16x16x32_bf16 v[94:97], v[160:163], v[192:195], v[94:97]
	v_mfma_f32_16x16x32_bf16 v[86:89], v[168:171], v[192:195], v[86:89]
	v_mfma_f32_16x16x32_bf16 v[78:81], v[160:163], v[206:209], v[78:81]
	v_mfma_f32_16x16x32_bf16 v[70:73], v[168:171], v[206:209], v[70:73]
	s_setprio 0
	s_barrier
	s_add_i32 s76, 0, 0x14000
	s_add_i32 s22, s75, s48
	v_add_u32_e32 v151, s76, v147
	v_lshl_add_u64 v[226:227], s[64:65], 0, v[0:1]
	s_mov_b32 m0, s22
	ds_read_b128 v[210:213], v151
	ds_read_b128 v[214:217], v151 offset:1024
	ds_read_b128 v[218:221], v151 offset:2048
	ds_read_b128 v[222:225], v151 offset:3072
	global_load_lds_dwordx4 v[226:227], off
	v_lshl_add_u64 v[240:241], s[64:65], 0, v[134:135]
	s_add_i32 m0, s22, 0x2000
	s_nop 0
	global_load_lds_dwordx4 v[240:241], off
	s_barrier
	s_waitcnt lgkmcnt(0)
	s_setprio 1
	s_waitcnt lgkmcnt(0)
	v_mfma_f32_16x16x32_bf16 v[122:125], v[210:213], v[172:175], v[122:125]
	v_mfma_f32_16x16x32_bf16 v[114:117], v[218:221], v[172:175], v[114:117]
	v_mfma_f32_16x16x32_bf16 v[106:109], v[210:213], v[180:183], v[106:109]
	v_mfma_f32_16x16x32_bf16 v[98:101], v[218:221], v[180:183], v[98:101]
	v_mfma_f32_16x16x32_bf16 v[90:93], v[210:213], v[188:191], v[90:93]
	v_mfma_f32_16x16x32_bf16 v[82:85], v[218:221], v[188:191], v[82:85]
	v_mfma_f32_16x16x32_bf16 v[74:77], v[210:213], v[202:205], v[74:77]
	v_mfma_f32_16x16x32_bf16 v[66:69], v[218:221], v[202:205], v[66:69]
	v_mfma_f32_16x16x32_bf16 v[122:125], v[214:217], v[176:179], v[122:125]
	v_mfma_f32_16x16x32_bf16 v[114:117], v[222:225], v[176:179], v[114:117]
	v_mfma_f32_16x16x32_bf16 v[106:109], v[214:217], v[184:187], v[106:109]
	v_mfma_f32_16x16x32_bf16 v[98:101], v[222:225], v[184:187], v[98:101]
	v_mfma_f32_16x16x32_bf16 v[90:93], v[214:217], v[192:195], v[90:93]
	v_mfma_f32_16x16x32_bf16 v[82:85], v[222:225], v[192:195], v[82:85]
	v_mfma_f32_16x16x32_bf16 v[74:77], v[214:217], v[206:209], v[74:77]
	v_mfma_f32_16x16x32_bf16 v[66:69], v[222:225], v[206:209], v[66:69]
	s_setprio 0
	s_mov_b32 m0, s50
	v_lshl_add_u64 v[242:243], s[66:67], 0, v[130:131]
	s_barrier
	ds_read_b128 v[172:175], v149 offset:16384
	ds_read_b128 v[176:179], v149 offset:17408
	ds_read_b128 v[180:183], v149 offset:18432
	ds_read_b128 v[184:187], v149 offset:19456
	ds_read_b128 v[188:191], v149 offset:20480
	ds_read_b128 v[192:195], v149 offset:21504
	ds_read_b128 v[202:205], v149 offset:22528
	ds_read_b128 v[206:209], v149 offset:23552
	global_load_lds_dwordx4 v[242:243], off
	v_lshl_add_u64 v[244:245], s[66:67], 0, v[132:133]
	s_mov_b32 m0, s51
	s_nop 0
	global_load_lds_dwordx4 v[244:245], off
	s_barrier
	s_waitcnt lgkmcnt(0)
	s_setprio 1
	s_waitcnt lgkmcnt(0)
	v_mfma_f32_16x16x32_bf16 v[62:65], v[156:159], v[172:175], v[62:65]
	v_mfma_f32_16x16x32_bf16 v[54:57], v[164:167], v[172:175], v[54:57]
	v_mfma_f32_16x16x32_bf16 v[46:49], v[156:159], v[180:183], v[46:49]
	v_mfma_f32_16x16x32_bf16 v[38:41], v[164:167], v[180:183], v[38:41]
	v_mfma_f32_16x16x32_bf16 v[30:33], v[156:159], v[188:191], v[30:33]
	v_mfma_f32_16x16x32_bf16 v[22:25], v[164:167], v[188:191], v[22:25]
	v_mfma_f32_16x16x32_bf16 v[14:17], v[156:159], v[202:205], v[14:17]
	v_mfma_f32_16x16x32_bf16 v[6:9], v[164:167], v[202:205], v[6:9]
	v_mfma_f32_16x16x32_bf16 v[62:65], v[160:163], v[176:179], v[62:65]
	v_mfma_f32_16x16x32_bf16 v[54:57], v[168:171], v[176:179], v[54:57]
	v_mfma_f32_16x16x32_bf16 v[46:49], v[160:163], v[184:187], v[46:49]
	v_mfma_f32_16x16x32_bf16 v[38:41], v[168:171], v[184:187], v[38:41]
	v_mfma_f32_16x16x32_bf16 v[30:33], v[160:163], v[192:195], v[30:33]
	v_mfma_f32_16x16x32_bf16 v[22:25], v[168:171], v[192:195], v[22:25]
	v_mfma_f32_16x16x32_bf16 v[14:17], v[160:163], v[206:209], v[14:17]
	v_mfma_f32_16x16x32_bf16 v[6:9], v[168:171], v[206:209], v[6:9]
	s_setprio 0
	s_barrier
; #define PG8_STAGE(bufoff, gbase, voff) do { _Pragma("unroll") for (int _i = 0; _i < 2; ++_i) \
;         __builtin_amdgcn_global_load_lds((const unsigned*)((const char*)(gbase) + (voff)[_i]), (LAS unsigned*)(lds + (bufoff) + ldsw + _i * 8192), 16, 0, 0); } while (0)
; #define PG8_LDA(dst, b, h) do { _Pragma("unroll") for (int m = 0; m < 4; ++m) _Pragma("unroll") for (int k = 0; k < 2; ++k) dst[m][k] = *(const LAS bf16x8*)(lds + PG8_SA(b, h) + aoff + m * 2048 + k * 1024); } while (0)
; #define PG8_LDB(dst, b, h) do { _Pragma("unroll") for (int n = 0; n < 2; ++n) _Pragma("unroll") for (int k = 0; k < 2; ++k) dst[n][k] = *(const LAS bf16x8*)(lds + PG8_SB(b, h) + boff + n * 2048 + k * 1024); } while (0)
; #define PG8_MMA(ai, bj, At, Bt) do { __builtin_amdgcn_s_setprio(1); _Pragma("unroll") for (int m = 0; m < 4; ++m) _Pragma("unroll") for (int n = 0; n < 2; ++n) _Pragma("unroll") for (int k = 0; k < 2; ++k) \
;         acc[ai][bj][m][n] = __builtin_amdgcn_mfma_f32_16x16x32_bf16(Bt[n][k], At[m][k], acc[ai][bj][m][n], 0, 0, 0); __builtin_amdgcn_s_setprio(0); } while (0)
; #define PG8_WAIT_V(n) asm volatile("s_waitcnt vmcnt(" #n ")" ::: "memory")
; #define PG8_WAIT_L(n) asm volatile("s_waitcnt lgkmcnt(" #n ")" ::: "memory")
; #define PG8_BAR __builtin_amdgcn_s_barrier()
; #define PG8_SCHED __builtin_amdgcn_sched_barrier(0)
; template <class Epi>
; __device__ __forceinline__ void gemm_phase(LAS unsigned char* lds, const Gemm g, const StaticOrder& S, const Epi& E) {
;     ...
;             PG8_STAGE(PG8_SB(0, 1), b2 + hB, voffB);
;             PG8_WAIT_V(6); PG8_BAR; PG8_MMA(1, 1, At, B1); PG8_BAR;
;             PG8_LDB(B0, 1, 0); PG8_SCHED; PG8_LDA(At, 1, 0); PG8_STAGE(PG8_SA(0, 1), a2 + hA, voffA);
;             PG8_WAIT_L(8); PG8_BAR; PG8_WAIT_L(0); PG8_MMA(0, 0, At, B0); PG8_BAR; PG8_SCHED;
;             PG8_LDB(B1, 1, 1); PG8_STAGE(PG8_SB(1, 0), b3, voffB);
;             PG8_BAR; PG8_WAIT_L(0); PG8_MMA(0, 1, At, B1); PG8_BAR;
;             PG8_LDA(At, 1, 1); PG8_STAGE(PG8_SA(1, 0), a3, voffA);
;             PG8_BAR; PG8_WAIT_L(0); PG8_MMA(1, 0, At, B0); PG8_BAR; PG8_SCHED;
	s_add_u32 s22, s64, 0x40000
	s_addc_u32 s23, s65, 0
	s_add_i32 s75, s76, s48
	v_lshl_add_u64 v[156:157], s[22:23], 0, v[0:1]
	s_mov_b32 m0, s75
	s_nop 0
	global_load_lds_dwordx4 v[156:157], off
	v_lshl_add_u64 v[156:157], s[22:23], 0, v[134:135]
	s_add_i32 m0, s75, 0x2000
	s_nop 0
	global_load_lds_dwordx4 v[156:157], off
	s_waitcnt vmcnt(6)
	s_barrier
	s_setprio 1
	v_mfma_f32_16x16x32_bf16 v[58:61], v[210:213], v[172:175], v[58:61]
	v_mfma_f32_16x16x32_bf16 v[50:53], v[218:221], v[172:175], v[50:53]
	v_mfma_f32_16x16x32_bf16 v[42:45], v[210:213], v[180:183], v[42:45]
	v_mfma_f32_16x16x32_bf16 v[34:37], v[218:221], v[180:183], v[34:37]
	v_mfma_f32_16x16x32_bf16 v[26:29], v[210:213], v[188:191], v[26:29]
	v_mfma_f32_16x16x32_bf16 v[18:21], v[218:221], v[188:191], v[18:21]
	v_mfma_f32_16x16x32_bf16 v[10:13], v[210:213], v[202:205], v[10:13]
	v_mfma_f32_16x16x32_bf16 v[2:5], v[218:221], v[202:205], v[2:5]
	v_mfma_f32_16x16x32_bf16 v[58:61], v[214:217], v[176:179], v[58:61]
	v_mfma_f32_16x16x32_bf16 v[50:53], v[222:225], v[176:179], v[50:53]
	v_mfma_f32_16x16x32_bf16 v[42:45], v[214:217], v[184:187], v[42:45]
	v_mfma_f32_16x16x32_bf16 v[34:37], v[222:225], v[184:187], v[34:37]
	v_mfma_f32_16x16x32_bf16 v[26:29], v[214:217], v[192:195], v[26:29]
	v_mfma_f32_16x16x32_bf16 v[18:21], v[222:225], v[192:195], v[18:21]
	v_mfma_f32_16x16x32_bf16 v[10:13], v[214:217], v[206:209], v[10:13]
	v_mfma_f32_16x16x32_bf16 v[2:5], v[222:225], v[206:209], v[2:5]
	s_setprio 0
	s_add_i32 s75, 0, 0x18000
	v_add_u32_e32 v151, s75, v147
	s_barrier
	ds_read_b128 v[156:159], v151
	ds_read_b128 v[160:163], v151 offset:1024
	ds_read_b128 v[164:167], v151 offset:2048
	ds_read_b128 v[168:171], v151 offset:3072
	s_add_u32 s22, s66, 0x40000
	s_addc_u32 s23, s67, 0
	s_mov_b32 m0, s53
	v_lshl_add_u64 v[210:211], s[22:23], 0, v[130:131]
	ds_read_b128 v[172:175], v149 offset:32768
	ds_read_b128 v[176:179], v149 offset:33792
	ds_read_b128 v[180:183], v149 offset:34816
	ds_read_b128 v[184:187], v149 offset:35840
	ds_read_b128 v[188:191], v149 offset:36864
	ds_read_b128 v[192:195], v149 offset:37888
	ds_read_b128 v[202:205], v149 offset:38912
	ds_read_b128 v[206:209], v149 offset:39936
	global_load_lds_dwordx4 v[210:211], off
	v_lshl_add_u64 v[210:211], s[22:23], 0, v[132:133]
	s_mov_b32 m0, s54
	s_nop 0
	global_load_lds_dwordx4 v[210:211], off
	s_waitcnt lgkmcnt(8)
	s_barrier
	s_waitcnt lgkmcnt(0)
	s_setprio 1
	s_waitcnt lgkmcnt(0)
	v_mfma_f32_16x16x32_bf16 v[126:129], v[156:159], v[172:175], v[126:129]
	v_mfma_f32_16x16x32_bf16 v[118:121], v[164:167], v[172:175], v[118:121]
	v_mfma_f32_16x16x32_bf16 v[110:113], v[156:159], v[180:183], v[110:113]
	v_mfma_f32_16x16x32_bf16 v[102:105], v[164:167], v[180:183], v[102:105]
	v_mfma_f32_16x16x32_bf16 v[94:97], v[156:159], v[188:191], v[94:97]
	v_mfma_f32_16x16x32_bf16 v[86:89], v[164:167], v[188:191], v[86:89]
	v_mfma_f32_16x16x32_bf16 v[78:81], v[156:159], v[202:205], v[78:81]
	v_mfma_f32_16x16x32_bf16 v[70:73], v[164:167], v[202:205], v[70:73]
	v_mfma_f32_16x16x32_bf16 v[126:129], v[160:163], v[176:179], v[126:129]
	v_mfma_f32_16x16x32_bf16 v[118:121], v[168:171], v[176:179], v[118:121]
	v_mfma_f32_16x16x32_bf16 v[110:113], v[160:163], v[184:187], v[110:113]
	v_mfma_f32_16x16x32_bf16 v[102:105], v[168:171], v[184:187], v[102:105]
	v_mfma_f32_16x16x32_bf16 v[94:97], v[160:163], v[192:195], v[94:97]
	v_mfma_f32_16x16x32_bf16 v[86:89], v[168:171], v[192:195], v[86:89]
	v_mfma_f32_16x16x32_bf16 v[78:81], v[160:163], v[206:209], v[78:81]
	v_mfma_f32_16x16x32_bf16 v[70:73], v[168:171], v[206:209], v[70:73]
	s_setprio 0
	s_barrier
	s_add_i32 s66, 0, 0x1c000
	s_add_i32 s22, s75, s48
	v_add_u32_e32 v151, s66, v147
	v_lshl_add_u64 v[226:227], v[226:227], 0, s[34:35]
	s_mov_b32 m0, s22
	ds_read_b128 v[210:213], v151
	ds_read_b128 v[214:217], v151 offset:1024
	ds_read_b128 v[218:221], v151 offset:2048
	ds_read_b128 v[222:225], v151 offset:3072
	global_load_lds_dwordx4 v[226:227], off
	v_lshl_add_u64 v[226:227], v[240:241], 0, s[34:35]
	s_add_i32 m0, s22, 0x2000
	s_nop 0
	global_load_lds_dwordx4 v[226:227], off
	s_barrier
	s_waitcnt lgkmcnt(0)
	s_setprio 1
	s_waitcnt lgkmcnt(0)
	v_mfma_f32_16x16x32_bf16 v[122:125], v[210:213], v[172:175], v[122:125]
	v_mfma_f32_16x16x32_bf16 v[114:117], v[218:221], v[172:175], v[114:117]
	v_mfma_f32_16x16x32_bf16 v[106:109], v[210:213], v[180:183], v[106:109]
	v_mfma_f32_16x16x32_bf16 v[98:101], v[218:221], v[180:183], v[98:101]
	v_mfma_f32_16x16x32_bf16 v[90:93], v[210:213], v[188:191], v[90:93]
	v_mfma_f32_16x16x32_bf16 v[82:85], v[218:221], v[188:191], v[82:85]
	v_mfma_f32_16x16x32_bf16 v[74:77], v[210:213], v[202:205], v[74:77]
	v_mfma_f32_16x16x32_bf16 v[66:69], v[218:221], v[202:205], v[66:69]
	v_mfma_f32_16x16x32_bf16 v[122:125], v[214:217], v[176:179], v[122:125]
	v_mfma_f32_16x16x32_bf16 v[114:117], v[222:225], v[176:179], v[114:117]
	v_mfma_f32_16x16x32_bf16 v[106:109], v[214:217], v[184:187], v[106:109]
	v_mfma_f32_16x16x32_bf16 v[98:101], v[222:225], v[184:187], v[98:101]
	v_mfma_f32_16x16x32_bf16 v[90:93], v[214:217], v[192:195], v[90:93]
	v_mfma_f32_16x16x32_bf16 v[82:85], v[222:225], v[192:195], v[82:85]
	v_mfma_f32_16x16x32_bf16 v[74:77], v[214:217], v[206:209], v[74:77]
	v_mfma_f32_16x16x32_bf16 v[66:69], v[222:225], v[206:209], v[66:69]
	s_setprio 0
	s_mov_b32 m0, s56
	v_lshl_add_u64 v[226:227], v[242:243], 0, s[34:35]
	s_barrier
	ds_read_b128 v[172:175], v149 offset:49152
	ds_read_b128 v[176:179], v149 offset:50176
	ds_read_b128 v[180:183], v149 offset:51200
	ds_read_b128 v[184:187], v149 offset:52224
	ds_read_b128 v[188:191], v149 offset:53248
	ds_read_b128 v[192:195], v149 offset:54272
	ds_read_b128 v[202:205], v149 offset:55296
	ds_read_b128 v[206:209], v149 offset:56320
	global_load_lds_dwordx4 v[226:227], off
	v_lshl_add_u64 v[226:227], v[244:245], 0, s[34:35]
	s_mov_b32 m0, s57
	s_nop 0
	global_load_lds_dwordx4 v[226:227], off
	s_barrier
; __device__ __forceinline__ float siluf_(float x) { return x * sigmoidf_(x); }
; #define PG8_STAGE(bufoff, gbase, voff) do { _Pragma("unroll") for (int _i = 0; _i < 2; ++_i) \
;         __builtin_amdgcn_global_load_lds((const unsigned*)((const char*)(gbase) + (voff)[_i]), (LAS unsigned*)(lds + (bufoff) + ldsw + _i * 8192), 16, 0, 0); } while (0)
; #define PG8_MMA(ai, bj, At, Bt) do { __builtin_amdgcn_s_setprio(1); _Pragma("unroll") for (int m = 0; m < 4; ++m) _Pragma("unroll") for (int n = 0; n < 2; ++n) _Pragma("unroll") for (int k = 0; k < 2; ++k) \
;         acc[ai][bj][m][n] = __builtin_amdgcn_mfma_f32_16x16x32_bf16(Bt[n][k], At[m][k], acc[ai][bj][m][n], 0, 0, 0); __builtin_amdgcn_s_setprio(0); } while (0)
; #define PG8_WAIT_V(n) asm volatile("s_waitcnt vmcnt(" #n ")" ::: "memory")
; #define PG8_WAIT_L(n) asm volatile("s_waitcnt lgkmcnt(" #n ")" ::: "memory")
; #define PG8_BAR __builtin_amdgcn_s_barrier()
; #define PG8_SCHED __builtin_amdgcn_sched_barrier(0)
; template <class Epi>
; __device__ __forceinline__ void gemm_phase(LAS unsigned char* lds, const Gemm g, const StaticOrder& S, const Epi& E) {
;     ...
;             PG8_BAR; PG8_WAIT_L(0); PG8_MMA(1, 0, At, B0); PG8_BAR; PG8_SCHED;
;             PG8_STAGE(PG8_SB(1, 1), b3 + hB, voffB);
;             PG8_WAIT_V(6); PG8_BAR; PG8_MMA(1, 1, At, B1); PG8_BAR;
;         }
;         if constexpr (Epi::HAS_PRE) { E(acc, cur, wr, wc, fr, fq, pre); if (has_next) E.pre(pre, nxt, wr, fr); } else E(acc, cur, wr, wc, fr, fq);
;         if (!has_next) break;
;     __device__ __forceinline__ void operator()(const Acc& acc, const Unit& u, int wr, int wc, int fr, int fq, const RsPre& pr) const {
;         asm volatile("" : "+v"(fr), "+v"(fq));
;         const int row0 = u.pm * 256 + wr * 64 + fr, col0 = u.pn * 128 + wc * 32 + 8 * fq;
;         const float (&rs)[2][4] = pr.rs;
; #pragma unroll
;         for (int ai = 0; ai < 2; ++ai)
; #pragma unroll
;             for (int m = 0; m < 4; ++m) { f32x4 o[2];
; #pragma unroll
;                 for (int n = 0; n < 2; ++n) { const f32x4 a1 = acc[ai][0][m][n] * rs[ai][m], a3 = acc[ai][1][m][n] * rs[ai][m];
;                     o[n] = (f32x4){siluf_(a1[0]) * a3[0], siluf_(a1[1]) * a3[1], siluf_(a1[2]) * a3[2], siluf_(a1[3]) * a3[3]}; }
;                 *(u32x4*)(ff + (size_t)(row0 + ai * 128 + m * 16) * DFF + col0) = pack8(o[0], o[1]); }
	s_waitcnt lgkmcnt(0)
	s_setprio 1
	s_waitcnt lgkmcnt(0)
	v_mfma_f32_16x16x32_bf16 v[62:65], v[156:159], v[172:175], v[62:65]
	v_mfma_f32_16x16x32_bf16 v[54:57], v[164:167], v[172:175], v[54:57]
	v_mfma_f32_16x16x32_bf16 v[46:49], v[156:159], v[180:183], v[46:49]
	v_mfma_f32_16x16x32_bf16 v[38:41], v[164:167], v[180:183], v[38:41]
	v_mfma_f32_16x16x32_bf16 v[30:33], v[156:159], v[188:191], v[30:33]
	v_mfma_f32_16x16x32_bf16 v[22:25], v[164:167], v[188:191], v[22:25]
	v_mfma_f32_16x16x32_bf16 v[14:17], v[156:159], v[202:205], v[14:17]
	v_mfma_f32_16x16x32_bf16 v[6:9], v[164:167], v[202:205], v[6:9]
	v_mfma_f32_16x16x32_bf16 v[62:65], v[160:163], v[176:179], v[62:65]
	v_mfma_f32_16x16x32_bf16 v[54:57], v[168:171], v[176:179], v[54:57]
	v_mfma_f32_16x16x32_bf16 v[46:49], v[160:163], v[184:187], v[46:49]
	v_mfma_f32_16x16x32_bf16 v[38:41], v[168:171], v[184:187], v[38:41]
	v_mfma_f32_16x16x32_bf16 v[30:33], v[160:163], v[192:195], v[30:33]
	v_mfma_f32_16x16x32_bf16 v[22:25], v[168:171], v[192:195], v[22:25]
	v_mfma_f32_16x16x32_bf16 v[14:17], v[160:163], v[206:209], v[14:17]
	v_mfma_f32_16x16x32_bf16 v[6:9], v[168:171], v[206:209], v[6:9]
	s_setprio 0
	s_barrier
	s_add_u32 s22, s64, 0x40080
	s_addc_u32 s23, s65, 0
	s_add_i32 s64, s66, s48
	v_lshl_add_u64 v[156:157], s[22:23], 0, v[0:1]
	s_mov_b32 m0, s64
	s_nop 0
	global_load_lds_dwordx4 v[156:157], off
	v_lshl_add_u64 v[156:157], s[22:23], 0, v[134:135]
	s_add_i32 m0, s64, 0x2000
	s_nop 0
	global_load_lds_dwordx4 v[156:157], off
	s_waitcnt vmcnt(6)
	s_barrier
	s_setprio 1
	v_mfma_f32_16x16x32_bf16 v[58:61], v[210:213], v[172:175], v[58:61]
	v_mfma_f32_16x16x32_bf16 v[50:53], v[218:221], v[172:175], v[50:53]
	v_mfma_f32_16x16x32_bf16 v[42:45], v[210:213], v[180:183], v[42:45]
	v_mfma_f32_16x16x32_bf16 v[34:37], v[218:221], v[180:183], v[34:37]
	v_mfma_f32_16x16x32_bf16 v[26:29], v[210:213], v[188:191], v[26:29]
	v_mfma_f32_16x16x32_bf16 v[18:21], v[218:221], v[188:191], v[18:21]
	v_mfma_f32_16x16x32_bf16 v[10:13], v[210:213], v[202:205], v[10:13]
	v_mfma_f32_16x16x32_bf16 v[2:5], v[218:221], v[202:205], v[2:5]
	v_mfma_f32_16x16x32_bf16 v[58:61], v[214:217], v[176:179], v[58:61]
	v_mfma_f32_16x16x32_bf16 v[50:53], v[222:225], v[176:179], v[50:53]
	v_mfma_f32_16x16x32_bf16 v[42:45], v[214:217], v[184:187], v[42:45]
	v_mfma_f32_16x16x32_bf16 v[34:37], v[222:225], v[184:187], v[34:37]
	v_mfma_f32_16x16x32_bf16 v[26:29], v[214:217], v[192:195], v[26:29]
	v_mfma_f32_16x16x32_bf16 v[18:21], v[222:225], v[192:195], v[18:21]
	v_mfma_f32_16x16x32_bf16 v[10:13], v[214:217], v[206:209], v[10:13]
	v_mfma_f32_16x16x32_bf16 v[2:5], v[222:225], v[206:209], v[2:5]
	s_setprio 0
	s_add_i32 s74, s74, 2
	s_add_u32 s62, s62, 0x100
	s_addc_u32 s63, s63, 0
	s_add_u32 s70, s70, 0x100
	s_addc_u32 s71, s71, 0
	s_cmp_gt_u32 s74, 13
	s_barrier
	s_cbranch_scc0 .LBB0_104
	v_mov_b32_e32 v151, v137
	v_mov_b32_e32 v153, v143
	s_lshl_b32 s22, s60, 8
	s_add_i32 s22, s22, s49
	v_add_u32_e32 v151, s22, v151
	s_lshl_b32 s22, s33, 7
	s_or_b32 s22, s22, s55
	s_waitcnt vmcnt(6)
	v_pk_mul_f32 v[126:127], v[154:155], v[126:127] op_sel_hi:[0,1]
	v_lshl_add_u32 v156, v153, 3, s22
	v_mul_f32_e32 v153, 0xbfb8aa3b, v126
	v_exp_f32_e32 v153, v153
	v_pk_mul_f32 v[128:129], v[154:155], v[128:129] op_sel_hi:[0,1]
	v_pk_mul_f32 v[122:123], v[154:155], v[122:123] op_sel_hi:[0,1]
	v_pk_mul_f32 v[124:125], v[154:155], v[124:125] op_sel_hi:[0,1]
	v_add_f32_e32 v153, 1.0, v153
	v_rcp_f32_e32 v158, v153
	v_mul_f32_e32 v153, 0xbfb8aa3b, v127
	v_exp_f32_e32 v153, v153
	v_pk_mul_f32 v[118:119], v[154:155], v[118:119] op_sel_hi:[0,1]
	v_pk_mul_f32 v[120:121], v[154:155], v[120:121] op_sel_hi:[0,1]
	v_pk_mul_f32 v[114:115], v[154:155], v[114:115] op_sel_hi:[0,1]
	v_add_f32_e32 v153, 1.0, v153
	v_rcp_f32_e32 v159, v153
	v_pk_mul_f32 v[116:117], v[154:155], v[116:117] op_sel_hi:[0,1]
	v_ashrrev_i32_e32 v157, 31, v156
	s_movk_i32 s0, 0x1600
	v_pk_mul_f32 v[126:127], v[126:127], v[158:159]
	v_pk_mul_f32 v[110:111], v[152:153], v[110:111] op_sel_hi:[0,1]
	v_pk_mul_f32 v[122:123], v[126:127], v[122:123]
	v_mul_f32_e32 v126, 0xbfb8aa3b, v128
	v_mul_f32_e32 v127, 0xbfb8aa3b, v129
	v_exp_f32_e32 v126, v126
	v_exp_f32_e32 v127, v127
	v_pk_mul_f32 v[112:113], v[152:153], v[112:113] op_sel_hi:[0,1]
	v_pk_mul_f32 v[106:107], v[152:153], v[106:107] op_sel_hi:[0,1]
	v_add_f32_e32 v126, 1.0, v126
	v_add_f32_e32 v127, 1.0, v127
	v_rcp_f32_e32 v126, v126
	v_rcp_f32_e32 v127, v127
	v_pk_mul_f32 v[108:109], v[152:153], v[108:109] op_sel_hi:[0,1]
	v_pk_mul_f32 v[102:103], v[152:153], v[102:103] op_sel_hi:[0,1]
	v_pk_mul_f32 v[104:105], v[152:153], v[104:105] op_sel_hi:[0,1]
	v_pk_mul_f32 v[126:127], v[128:129], v[126:127]
	v_pk_mul_f32 v[98:99], v[152:153], v[98:99] op_sel_hi:[0,1]
	v_pk_mul_f32 v[124:125], v[126:127], v[124:125]
	v_mul_f32_e32 v126, 0xbfb8aa3b, v118
	v_mul_f32_e32 v127, 0xbfb8aa3b, v119
	v_exp_f32_e32 v126, v126
	v_exp_f32_e32 v127, v127
	v_pk_mul_f32 v[100:101], v[152:153], v[100:101] op_sel_hi:[0,1]
	v_pk_mul_f32 v[94:95], v[150:151], v[94:95] op_sel_hi:[0,1]
	v_add_f32_e32 v126, 1.0, v126
	v_add_f32_e32 v127, 1.0, v127
	v_rcp_f32_e32 v126, v126
	v_rcp_f32_e32 v127, v127
	v_pk_mul_f32 v[96:97], v[150:151], v[96:97] op_sel_hi:[0,1]
	v_pk_mul_f32 v[90:91], v[150:151], v[90:91] op_sel_hi:[0,1]
	v_pk_mul_f32 v[92:93], v[150:151], v[92:93] op_sel_hi:[0,1]
	v_pk_mul_f32 v[118:119], v[118:119], v[126:127]
	v_pk_mul_f32 v[86:87], v[150:151], v[86:87] op_sel_hi:[0,1]
	v_pk_mul_f32 v[114:115], v[118:119], v[114:115]
	v_mul_f32_e32 v118, 0xbfb8aa3b, v120
	v_mul_f32_e32 v119, 0xbfb8aa3b, v121
	v_exp_f32_e32 v118, v118
	v_exp_f32_e32 v119, v119
; __device__ __forceinline__ float siluf_(float x) { return x * sigmoidf_(x); }
; __device__ __forceinline__ u32x4 pack8(const f32x4 a, const f32x4 b) { u32x4 w; w.x = cvt_pk_bf16(a[0], a[1]); w.y = cvt_pk_bf16(a[2], a[3]); w.z = cvt_pk_bf16(b[0], b[1]); w.w = cvt_pk_bf16(b[2], b[3]); return w; }
;     __device__ __forceinline__ void operator()(const Acc& acc, const Unit& u, int wr, int wc, int fr, int fq, const RsPre& pr) const {
;     ...
; #pragma unroll
;         for (int ai = 0; ai < 2; ++ai)
; #pragma unroll
;             for (int m = 0; m < 4; ++m) { f32x4 o[2];
; #pragma unroll
;                 for (int n = 0; n < 2; ++n) { const f32x4 a1 = acc[ai][0][m][n] * rs[ai][m], a3 = acc[ai][1][m][n] * rs[ai][m];
;                     o[n] = (f32x4){siluf_(a1[0]) * a3[0], siluf_(a1[1]) * a3[1], siluf_(a1[2]) * a3[2], siluf_(a1[3]) * a3[3]}; }
;                 *(u32x4*)(ff + (size_t)(row0 + ai * 128 + m * 16) * DFF + col0) = pack8(o[0], o[1]); }
	v_pk_mul_f32 v[88:89], v[150:151], v[88:89] op_sel_hi:[0,1]
	v_pk_mul_f32 v[82:83], v[150:151], v[82:83] op_sel_hi:[0,1]
	v_add_f32_e32 v118, 1.0, v118
	v_add_f32_e32 v119, 1.0, v119
	v_rcp_f32_e32 v118, v118
	v_rcp_f32_e32 v119, v119
	v_pk_mul_f32 v[84:85], v[150:151], v[84:85] op_sel_hi:[0,1]
	v_pk_mul_f32 v[78:79], v[148:149], v[78:79] op_sel_hi:[0,1]
	v_pk_mul_f32 v[80:81], v[148:149], v[80:81] op_sel_hi:[0,1]
	v_pk_mul_f32 v[118:119], v[120:121], v[118:119]
	v_cvt_pk_bf16_f32 v120, v114, v115
	v_pk_mul_f32 v[116:117], v[118:119], v[116:117]
	v_mov_b64_e32 v[114:115], s[20:21]
	v_cvt_pk_bf16_f32 v118, v122, v123
	v_cvt_pk_bf16_f32 v121, v116, v117
	v_mad_i64_i32 v[122:123], s[22:23], v151, s0, v[114:115]
	v_lshlrev_b64 v[116:117], 1, v[156:157]
	v_cvt_pk_bf16_f32 v119, v124, v125
	v_lshl_add_u64 v[122:123], v[122:123], 0, v[116:117]
	global_store_dwordx4 v[122:123], v[118:121], off
	v_pk_mul_f32 v[74:75], v[148:149], v[74:75] op_sel_hi:[0,1]
	v_pk_mul_f32 v[76:77], v[148:149], v[76:77] op_sel_hi:[0,1]
	v_mul_f32_e32 v118, 0xbfb8aa3b, v110
	v_mul_f32_e32 v119, 0xbfb8aa3b, v111
	v_exp_f32_e32 v118, v118
	v_exp_f32_e32 v119, v119
	v_pk_mul_f32 v[70:71], v[148:149], v[70:71] op_sel_hi:[0,1]
	v_pk_mul_f32 v[72:73], v[148:149], v[72:73] op_sel_hi:[0,1]
	v_add_f32_e32 v118, 1.0, v118
	v_add_f32_e32 v119, 1.0, v119
	v_rcp_f32_e32 v118, v118
	v_rcp_f32_e32 v119, v119
	v_pk_mul_f32 v[66:67], v[148:149], v[66:67] op_sel_hi:[0,1]
	v_pk_mul_f32 v[68:69], v[148:149], v[68:69] op_sel_hi:[0,1]
	v_pk_mul_f32 v[62:63], v[146:147], v[62:63] op_sel_hi:[0,1]
	v_pk_mul_f32 v[110:111], v[110:111], v[118:119]
	v_pk_mul_f32 v[64:65], v[146:147], v[64:65] op_sel_hi:[0,1]
	v_pk_mul_f32 v[106:107], v[110:111], v[106:107]
	v_mul_f32_e32 v110, 0xbfb8aa3b, v112
	v_mul_f32_e32 v111, 0xbfb8aa3b, v113
	v_exp_f32_e32 v110, v110
	v_exp_f32_e32 v111, v111
	v_pk_mul_f32 v[58:59], v[146:147], v[58:59] op_sel_hi:[0,1]
	v_pk_mul_f32 v[60:61], v[146:147], v[60:61] op_sel_hi:[0,1]
	v_add_f32_e32 v110, 1.0, v110
	v_add_f32_e32 v111, 1.0, v111
	v_rcp_f32_e32 v110, v110
	v_rcp_f32_e32 v111, v111
	v_pk_mul_f32 v[54:55], v[146:147], v[54:55] op_sel_hi:[0,1]
	v_pk_mul_f32 v[56:57], v[146:147], v[56:57] op_sel_hi:[0,1]
	v_pk_mul_f32 v[50:51], v[146:147], v[50:51] op_sel_hi:[0,1]
	v_pk_mul_f32 v[110:111], v[112:113], v[110:111]
	v_pk_mul_f32 v[52:53], v[146:147], v[52:53] op_sel_hi:[0,1]
	v_pk_mul_f32 v[108:109], v[110:111], v[108:109]
	v_mul_f32_e32 v110, 0xbfb8aa3b, v102
	v_mul_f32_e32 v111, 0xbfb8aa3b, v103
	v_exp_f32_e32 v110, v110
	v_exp_f32_e32 v111, v111
	v_pk_mul_f32 v[46:47], v[144:145], v[46:47] op_sel_hi:[0,1]
	v_pk_mul_f32 v[48:49], v[144:145], v[48:49] op_sel_hi:[0,1]
	v_add_f32_e32 v110, 1.0, v110
	v_add_f32_e32 v111, 1.0, v111
	v_rcp_f32_e32 v110, v110
	v_rcp_f32_e32 v111, v111
	v_pk_mul_f32 v[42:43], v[144:145], v[42:43] op_sel_hi:[0,1]
	v_pk_mul_f32 v[44:45], v[144:145], v[44:45] op_sel_hi:[0,1]
	v_pk_mul_f32 v[38:39], v[144:145], v[38:39] op_sel_hi:[0,1]
	v_pk_mul_f32 v[102:103], v[102:103], v[110:111]
	v_pk_mul_f32 v[40:41], v[144:145], v[40:41] op_sel_hi:[0,1]
	v_pk_mul_f32 v[102:103], v[102:103], v[98:99]
	v_mul_f32_e32 v98, 0xbfb8aa3b, v104
	v_mul_f32_e32 v99, 0xbfb8aa3b, v105
	v_exp_f32_e32 v98, v98
	v_exp_f32_e32 v99, v99
	v_pk_mul_f32 v[34:35], v[144:145], v[34:35] op_sel_hi:[0,1]
	v_pk_mul_f32 v[36:37], v[144:145], v[36:37] op_sel_hi:[0,1]
	v_add_f32_e32 v98, 1.0, v98
	v_add_f32_e32 v99, 1.0, v99
	v_rcp_f32_e32 v98, v98
	v_rcp_f32_e32 v99, v99
	v_pk_mul_f32 v[30:31], v[142:143], v[30:31] op_sel_hi:[0,1]
	v_pk_mul_f32 v[32:33], v[142:143], v[32:33] op_sel_hi:[0,1]
	v_pk_mul_f32 v[26:27], v[142:143], v[26:27] op_sel_hi:[0,1]
	v_pk_mul_f32 v[98:99], v[104:105], v[98:99]
	v_pk_mul_f32 v[28:29], v[142:143], v[28:29] op_sel_hi:[0,1]
	v_pk_mul_f32 v[104:105], v[98:99], v[100:101]
	v_cvt_pk_bf16_f32 v100, v102, v103
	v_add_u32_e32 v102, 16, v151
	v_mad_i64_i32 v[102:103], s[22:23], v102, s0, v[114:115]
	v_cvt_pk_bf16_f32 v98, v106, v107
	v_cvt_pk_bf16_f32 v99, v108, v109
	v_cvt_pk_bf16_f32 v101, v104, v105
	v_lshl_add_u64 v[102:103], v[102:103], 0, v[116:117]
	global_store_dwordx4 v[102:103], v[98:101], off
	v_pk_mul_f32 v[22:23], v[142:143], v[22:23] op_sel_hi:[0,1]
	v_pk_mul_f32 v[24:25], v[142:143], v[24:25] op_sel_hi:[0,1]
	v_mul_f32_e32 v98, 0xbfb8aa3b, v94
	v_mul_f32_e32 v99, 0xbfb8aa3b, v95
	v_exp_f32_e32 v98, v98
	v_exp_f32_e32 v99, v99
	v_pk_mul_f32 v[18:19], v[142:143], v[18:19] op_sel_hi:[0,1]
	v_pk_mul_f32 v[20:21], v[142:143], v[20:21] op_sel_hi:[0,1]
	v_add_f32_e32 v98, 1.0, v98
	v_add_f32_e32 v99, 1.0, v99
	v_rcp_f32_e32 v98, v98
	v_rcp_f32_e32 v99, v99
	v_pk_mul_f32 v[14:15], v[136:137], v[14:15] op_sel_hi:[0,1]
	v_pk_mul_f32 v[16:17], v[136:137], v[16:17] op_sel_hi:[0,1]
	v_pk_mul_f32 v[10:11], v[136:137], v[10:11] op_sel_hi:[0,1]
	v_pk_mul_f32 v[94:95], v[94:95], v[98:99]
	v_pk_mul_f32 v[12:13], v[136:137], v[12:13] op_sel_hi:[0,1]
	v_pk_mul_f32 v[90:91], v[94:95], v[90:91]
	v_mul_f32_e32 v94, 0xbfb8aa3b, v96
	v_mul_f32_e32 v95, 0xbfb8aa3b, v97
	v_exp_f32_e32 v94, v94
	v_exp_f32_e32 v95, v95
	v_pk_mul_f32 v[6:7], v[136:137], v[6:7] op_sel_hi:[0,1]
	v_pk_mul_f32 v[8:9], v[136:137], v[8:9] op_sel_hi:[0,1]
	v_add_f32_e32 v94, 1.0, v94
	v_add_f32_e32 v95, 1.0, v95
	v_rcp_f32_e32 v94, v94
	v_rcp_f32_e32 v95, v95
	v_pk_mul_f32 v[2:3], v[136:137], v[2:3] op_sel_hi:[0,1]
	v_pk_mul_f32 v[4:5], v[136:137], v[4:5] op_sel_hi:[0,1]
	s_mov_b64 s[60:61], -1
	v_pk_mul_f32 v[94:95], v[96:97], v[94:95]
	s_and_b64 vcc, vcc, exec
	v_pk_mul_f32 v[92:93], v[94:95], v[92:93]
	v_mul_f32_e32 v94, 0xbfb8aa3b, v86
	v_mul_f32_e32 v95, 0xbfb8aa3b, v87
	v_exp_f32_e32 v94, v94
; __device__ __forceinline__ float siluf_(float x) { return x * sigmoidf_(x); }
; __device__ __forceinline__ u32x4 pack8(const f32x4 a, const f32x4 b) { u32x4 w; w.x = cvt_pk_bf16(a[0], a[1]); w.y = cvt_pk_bf16(a[2], a[3]); w.z = cvt_pk_bf16(b[0], b[1]); w.w = cvt_pk_bf16(b[2], b[3]); return w; }
;     __device__ __forceinline__ void operator()(const Acc& acc, const Unit& u, int wr, int wc, int fr, int fq, const RsPre& pr) const {
;     ...
; #pragma unroll
;         for (int ai = 0; ai < 2; ++ai)
; #pragma unroll
;             for (int m = 0; m < 4; ++m) { f32x4 o[2];
; #pragma unroll
;                 for (int n = 0; n < 2; ++n) { const f32x4 a1 = acc[ai][0][m][n] * rs[ai][m], a3 = acc[ai][1][m][n] * rs[ai][m];
;                     o[n] = (f32x4){siluf_(a1[0]) * a3[0], siluf_(a1[1]) * a3[1], siluf_(a1[2]) * a3[2], siluf_(a1[3]) * a3[3]}; }
;                 *(u32x4*)(ff + (size_t)(row0 + ai * 128 + m * 16) * DFF + col0) = pack8(o[0], o[1]); }
	v_exp_f32_e32 v95, v95
	v_add_f32_e32 v94, 1.0, v94
	v_add_f32_e32 v95, 1.0, v95
	v_rcp_f32_e32 v94, v94
	v_rcp_f32_e32 v95, v95
	s_nop 0
	v_pk_mul_f32 v[86:87], v[86:87], v[94:95]
	s_nop 0
	v_pk_mul_f32 v[86:87], v[86:87], v[82:83]
	v_mul_f32_e32 v82, 0xbfb8aa3b, v88
	v_mul_f32_e32 v83, 0xbfb8aa3b, v89
	v_exp_f32_e32 v82, v82
	v_exp_f32_e32 v83, v83
	v_add_f32_e32 v82, 1.0, v82
	v_add_f32_e32 v83, 1.0, v83
	v_rcp_f32_e32 v82, v82
	v_rcp_f32_e32 v83, v83
	s_nop 0
	v_pk_mul_f32 v[82:83], v[88:89], v[82:83]
	s_nop 0
	v_pk_mul_f32 v[88:89], v[82:83], v[84:85]
	v_cvt_pk_bf16_f32 v84, v86, v87
	v_add_u32_e32 v86, 32, v151
	v_mad_i64_i32 v[86:87], s[22:23], v86, s0, v[114:115]
	v_cvt_pk_bf16_f32 v82, v90, v91
	v_cvt_pk_bf16_f32 v83, v92, v93
	v_cvt_pk_bf16_f32 v85, v88, v89
	v_lshl_add_u64 v[86:87], v[86:87], 0, v[116:117]
	global_store_dwordx4 v[86:87], v[82:85], off
	s_nop 1
	v_mul_f32_e32 v82, 0xbfb8aa3b, v78
	v_mul_f32_e32 v83, 0xbfb8aa3b, v79
	v_exp_f32_e32 v82, v82
	v_exp_f32_e32 v83, v83
	v_add_f32_e32 v82, 1.0, v82
	v_add_f32_e32 v83, 1.0, v83
	v_rcp_f32_e32 v82, v82
	v_rcp_f32_e32 v83, v83
	s_nop 0
	v_pk_mul_f32 v[78:79], v[78:79], v[82:83]
	s_nop 0
	v_pk_mul_f32 v[74:75], v[78:79], v[74:75]
	v_mul_f32_e32 v78, 0xbfb8aa3b, v80
	v_mul_f32_e32 v79, 0xbfb8aa3b, v81
	v_exp_f32_e32 v78, v78
	v_exp_f32_e32 v79, v79
	v_add_f32_e32 v78, 1.0, v78
	v_add_f32_e32 v79, 1.0, v79
	v_rcp_f32_e32 v78, v78
	v_rcp_f32_e32 v79, v79
	s_nop 0
	v_pk_mul_f32 v[78:79], v[80:81], v[78:79]
	s_nop 0
	v_pk_mul_f32 v[76:77], v[78:79], v[76:77]
	v_mul_f32_e32 v78, 0xbfb8aa3b, v70
	v_mul_f32_e32 v79, 0xbfb8aa3b, v71
	v_exp_f32_e32 v78, v78
	v_exp_f32_e32 v79, v79
	v_add_f32_e32 v78, 1.0, v78
	v_add_f32_e32 v79, 1.0, v79
	v_rcp_f32_e32 v78, v78
	v_rcp_f32_e32 v79, v79
	s_nop 0
	v_pk_mul_f32 v[70:71], v[70:71], v[78:79]
	s_nop 0
	v_pk_mul_f32 v[70:71], v[70:71], v[66:67]
	v_mul_f32_e32 v66, 0xbfb8aa3b, v72
	v_mul_f32_e32 v67, 0xbfb8aa3b, v73
	v_exp_f32_e32 v66, v66
	v_exp_f32_e32 v67, v67
	v_add_f32_e32 v66, 1.0, v66
	v_add_f32_e32 v67, 1.0, v67
	v_rcp_f32_e32 v66, v66
	v_rcp_f32_e32 v67, v67
	s_nop 0
	v_pk_mul_f32 v[66:67], v[72:73], v[66:67]
	s_nop 0
	v_pk_mul_f32 v[72:73], v[66:67], v[68:69]
	v_cvt_pk_bf16_f32 v68, v70, v71
	v_add_u32_e32 v70, 48, v151
	v_mad_i64_i32 v[70:71], s[22:23], v70, s0, v[114:115]
	v_cvt_pk_bf16_f32 v66, v74, v75
	v_cvt_pk_bf16_f32 v67, v76, v77
	v_cvt_pk_bf16_f32 v69, v72, v73
	v_lshl_add_u64 v[70:71], v[70:71], 0, v[116:117]
	global_store_dwordx4 v[70:71], v[66:69], off
	s_nop 1
	v_mul_f32_e32 v66, 0xbfb8aa3b, v62
	v_mul_f32_e32 v67, 0xbfb8aa3b, v63
	v_exp_f32_e32 v66, v66
	v_exp_f32_e32 v67, v67
	v_add_u32_e32 v68, 0x80, v151
	v_add_f32_e32 v66, 1.0, v66
	v_add_f32_e32 v67, 1.0, v67
	v_rcp_f32_e32 v66, v66
	v_rcp_f32_e32 v67, v67
	s_nop 0
	v_pk_mul_f32 v[62:63], v[62:63], v[66:67]
	s_nop 0
	v_pk_mul_f32 v[58:59], v[62:63], v[58:59]
	v_mul_f32_e32 v62, 0xbfb8aa3b, v64
	v_mul_f32_e32 v63, 0xbfb8aa3b, v65
	v_exp_f32_e32 v62, v62
	v_exp_f32_e32 v63, v63
	v_add_f32_e32 v62, 1.0, v62
	v_add_f32_e32 v63, 1.0, v63
	v_rcp_f32_e32 v62, v62
	v_rcp_f32_e32 v63, v63
	s_nop 0
	v_pk_mul_f32 v[62:63], v[64:65], v[62:63]
	s_nop 0
	v_pk_mul_f32 v[60:61], v[62:63], v[60:61]
	v_mul_f32_e32 v62, 0xbfb8aa3b, v54
	v_mul_f32_e32 v63, 0xbfb8aa3b, v55
	v_exp_f32_e32 v62, v62
	v_exp_f32_e32 v63, v63
	v_add_f32_e32 v62, 1.0, v62
	v_add_f32_e32 v63, 1.0, v63
	v_rcp_f32_e32 v62, v62
	v_rcp_f32_e32 v63, v63
	s_nop 0
	v_pk_mul_f32 v[54:55], v[54:55], v[62:63]
	s_nop 0
	v_pk_mul_f32 v[54:55], v[54:55], v[50:51]
	v_mul_f32_e32 v50, 0xbfb8aa3b, v56
	v_mul_f32_e32 v51, 0xbfb8aa3b, v57
	v_exp_f32_e32 v50, v50
	v_exp_f32_e32 v51, v51
	v_add_f32_e32 v50, 1.0, v50
	v_add_f32_e32 v51, 1.0, v51
	v_rcp_f32_e32 v50, v50
	v_rcp_f32_e32 v51, v51
	s_nop 0
	v_pk_mul_f32 v[50:51], v[56:57], v[50:51]
	s_nop 0
	v_pk_mul_f32 v[56:57], v[50:51], v[52:53]
	v_cvt_pk_bf16_f32 v52, v54, v55
	v_mad_i64_i32 v[54:55], s[22:23], v68, s0, v[114:115]
	v_cvt_pk_bf16_f32 v50, v58, v59
	v_cvt_pk_bf16_f32 v51, v60, v61
	v_cvt_pk_bf16_f32 v53, v56, v57
	v_lshl_add_u64 v[54:55], v[54:55], 0, v[116:117]
	global_store_dwordx4 v[54:55], v[50:53], off
	s_nop 1
	v_mul_f32_e32 v50, 0xbfb8aa3b, v46
	v_mul_f32_e32 v51, 0xbfb8aa3b, v47
	v_exp_f32_e32 v50, v50
	v_exp_f32_e32 v51, v51
	v_add_f32_e32 v50, 1.0, v50
	v_add_f32_e32 v51, 1.0, v51
	v_rcp_f32_e32 v50, v50
	v_rcp_f32_e32 v51, v51
	s_nop 0
	v_pk_mul_f32 v[46:47], v[46:47], v[50:51]
	s_nop 0
	v_pk_mul_f32 v[42:43], v[46:47], v[42:43]
	v_mul_f32_e32 v46, 0xbfb8aa3b, v48
	v_mul_f32_e32 v47, 0xbfb8aa3b, v49
	v_exp_f32_e32 v46, v46
	v_exp_f32_e32 v47, v47
	v_add_f32_e32 v46, 1.0, v46
	v_add_f32_e32 v47, 1.0, v47
	v_rcp_f32_e32 v46, v46
	v_rcp_f32_e32 v47, v47
	s_nop 0
	v_pk_mul_f32 v[46:47], v[48:49], v[46:47]
	s_nop 0
; __device__ __forceinline__ float siluf_(float x) { return x * sigmoidf_(x); }
; __device__ __forceinline__ u32x4 pack8(const f32x4 a, const f32x4 b) { u32x4 w; w.x = cvt_pk_bf16(a[0], a[1]); w.y = cvt_pk_bf16(a[2], a[3]); w.z = cvt_pk_bf16(b[0], b[1]); w.w = cvt_pk_bf16(b[2], b[3]); return w; }
;     __device__ __forceinline__ void pre(RsPre& r, const Unit& u, int wr, int fr) const {
; #pragma unroll
;         for (int ai = 0; ai < 2; ++ai)
; #pragma unroll
;             for (int m = 0; m < 4; ++m) r.rs[ai][m] = rsv[u.pm * 256 + wr * 64 + fr + ai * 128 + m * 16]; }
;     __device__ __forceinline__ void operator()(const Acc& acc, const Unit& u, int wr, int wc, int fr, int fq, const RsPre& pr) const {
;     ...
; #pragma unroll
;         for (int ai = 0; ai < 2; ++ai)
; #pragma unroll
;             for (int m = 0; m < 4; ++m) { f32x4 o[2];
; #pragma unroll
;                 for (int n = 0; n < 2; ++n) { const f32x4 a1 = acc[ai][0][m][n] * rs[ai][m], a3 = acc[ai][1][m][n] * rs[ai][m];
;                     o[n] = (f32x4){siluf_(a1[0]) * a3[0], siluf_(a1[1]) * a3[1], siluf_(a1[2]) * a3[2], siluf_(a1[3]) * a3[3]}; }
;                 *(u32x4*)(ff + (size_t)(row0 + ai * 128 + m * 16) * DFF + col0) = pack8(o[0], o[1]); }
	v_pk_mul_f32 v[44:45], v[46:47], v[44:45]
	v_mul_f32_e32 v46, 0xbfb8aa3b, v38
	v_mul_f32_e32 v47, 0xbfb8aa3b, v39
	v_exp_f32_e32 v46, v46
	v_exp_f32_e32 v47, v47
	v_add_f32_e32 v46, 1.0, v46
	v_add_f32_e32 v47, 1.0, v47
	v_rcp_f32_e32 v46, v46
	v_rcp_f32_e32 v47, v47
	s_nop 0
	v_pk_mul_f32 v[38:39], v[38:39], v[46:47]
	s_nop 0
	v_pk_mul_f32 v[38:39], v[38:39], v[34:35]
	v_mul_f32_e32 v34, 0xbfb8aa3b, v40
	v_mul_f32_e32 v35, 0xbfb8aa3b, v41
	v_exp_f32_e32 v34, v34
	v_exp_f32_e32 v35, v35
	v_add_f32_e32 v34, 1.0, v34
	v_add_f32_e32 v35, 1.0, v35
	v_rcp_f32_e32 v34, v34
	v_rcp_f32_e32 v35, v35
	s_nop 0
	v_pk_mul_f32 v[34:35], v[40:41], v[34:35]
	s_nop 0
	v_pk_mul_f32 v[40:41], v[34:35], v[36:37]
	v_cvt_pk_bf16_f32 v36, v38, v39
	v_add_u32_e32 v38, 0x90, v151
	v_mad_i64_i32 v[38:39], s[22:23], v38, s0, v[114:115]
	v_cvt_pk_bf16_f32 v34, v42, v43
	v_cvt_pk_bf16_f32 v35, v44, v45
	v_cvt_pk_bf16_f32 v37, v40, v41
	v_lshl_add_u64 v[38:39], v[38:39], 0, v[116:117]
	global_store_dwordx4 v[38:39], v[34:37], off
	s_nop 1
	v_mul_f32_e32 v34, 0xbfb8aa3b, v30
	v_mul_f32_e32 v35, 0xbfb8aa3b, v31
	v_exp_f32_e32 v34, v34
	v_exp_f32_e32 v35, v35
	v_add_f32_e32 v34, 1.0, v34
	v_add_f32_e32 v35, 1.0, v35
	v_rcp_f32_e32 v34, v34
	v_rcp_f32_e32 v35, v35
	s_nop 0
	v_pk_mul_f32 v[30:31], v[30:31], v[34:35]
	s_nop 0
	v_pk_mul_f32 v[26:27], v[30:31], v[26:27]
	v_mul_f32_e32 v30, 0xbfb8aa3b, v32
	v_mul_f32_e32 v31, 0xbfb8aa3b, v33
	v_exp_f32_e32 v30, v30
	v_exp_f32_e32 v31, v31
	v_add_f32_e32 v30, 1.0, v30
	v_add_f32_e32 v31, 1.0, v31
	v_rcp_f32_e32 v30, v30
	v_rcp_f32_e32 v31, v31
	s_nop 0
	v_pk_mul_f32 v[30:31], v[32:33], v[30:31]
	s_nop 0
	v_pk_mul_f32 v[28:29], v[30:31], v[28:29]
	v_mul_f32_e32 v30, 0xbfb8aa3b, v22
	v_mul_f32_e32 v31, 0xbfb8aa3b, v23
	v_exp_f32_e32 v30, v30
	v_exp_f32_e32 v31, v31
	v_add_f32_e32 v30, 1.0, v30
	v_add_f32_e32 v31, 1.0, v31
	v_rcp_f32_e32 v30, v30
	v_rcp_f32_e32 v31, v31
	s_nop 0
	v_pk_mul_f32 v[22:23], v[22:23], v[30:31]
	s_nop 0
	v_pk_mul_f32 v[22:23], v[22:23], v[18:19]
	v_mul_f32_e32 v18, 0xbfb8aa3b, v24
	v_mul_f32_e32 v19, 0xbfb8aa3b, v25
	v_exp_f32_e32 v18, v18
	v_exp_f32_e32 v19, v19
	v_add_f32_e32 v18, 1.0, v18
	v_add_f32_e32 v19, 1.0, v19
	v_rcp_f32_e32 v18, v18
	v_rcp_f32_e32 v19, v19
	s_nop 0
	v_pk_mul_f32 v[18:19], v[24:25], v[18:19]
	s_nop 0
	v_pk_mul_f32 v[24:25], v[18:19], v[20:21]
	v_cvt_pk_bf16_f32 v20, v22, v23
	v_add_u32_e32 v22, 0xa0, v151
	v_mad_i64_i32 v[22:23], s[22:23], v22, s0, v[114:115]
	v_cvt_pk_bf16_f32 v18, v26, v27
	v_cvt_pk_bf16_f32 v19, v28, v29
	v_cvt_pk_bf16_f32 v21, v24, v25
	v_lshl_add_u64 v[22:23], v[22:23], 0, v[116:117]
	global_store_dwordx4 v[22:23], v[18:21], off
	s_nop 1
	v_mul_f32_e32 v18, 0xbfb8aa3b, v14
	v_mul_f32_e32 v19, 0xbfb8aa3b, v15
	v_exp_f32_e32 v18, v18
	v_exp_f32_e32 v19, v19
	v_add_f32_e32 v18, 1.0, v18
	v_add_f32_e32 v19, 1.0, v19
	v_rcp_f32_e32 v18, v18
	v_rcp_f32_e32 v19, v19
	s_nop 0
	v_pk_mul_f32 v[14:15], v[14:15], v[18:19]
	s_nop 0
	v_pk_mul_f32 v[10:11], v[14:15], v[10:11]
	v_mul_f32_e32 v14, 0xbfb8aa3b, v16
	v_mul_f32_e32 v15, 0xbfb8aa3b, v17
	v_exp_f32_e32 v14, v14
	v_exp_f32_e32 v15, v15
	v_add_f32_e32 v14, 1.0, v14
	v_add_f32_e32 v15, 1.0, v15
	v_rcp_f32_e32 v14, v14
	v_rcp_f32_e32 v15, v15
	s_nop 0
	v_pk_mul_f32 v[14:15], v[16:17], v[14:15]
	s_nop 0
	v_pk_mul_f32 v[12:13], v[14:15], v[12:13]
	v_mul_f32_e32 v14, 0xbfb8aa3b, v6
	v_mul_f32_e32 v15, 0xbfb8aa3b, v7
	v_exp_f32_e32 v14, v14
	v_exp_f32_e32 v15, v15
	v_add_f32_e32 v14, 1.0, v14
	v_add_f32_e32 v15, 1.0, v15
	v_rcp_f32_e32 v14, v14
	v_rcp_f32_e32 v15, v15
	s_nop 0
	v_pk_mul_f32 v[6:7], v[6:7], v[14:15]
	s_nop 0
	v_pk_mul_f32 v[6:7], v[6:7], v[2:3]
	v_mul_f32_e32 v2, 0xbfb8aa3b, v8
	v_mul_f32_e32 v3, 0xbfb8aa3b, v9
	v_exp_f32_e32 v2, v2
	v_exp_f32_e32 v3, v3
	v_add_f32_e32 v2, 1.0, v2
	v_add_f32_e32 v3, 1.0, v3
	v_rcp_f32_e32 v2, v2
	v_rcp_f32_e32 v3, v3
	s_nop 0
	v_pk_mul_f32 v[2:3], v[8:9], v[2:3]
	s_nop 0
	v_pk_mul_f32 v[8:9], v[2:3], v[4:5]
	v_cvt_pk_bf16_f32 v4, v6, v7
	v_add_u32_e32 v6, 0xb0, v151
	v_mad_i64_i32 v[6:7], s[22:23], v6, s0, v[114:115]
	v_cvt_pk_bf16_f32 v2, v10, v11
	v_cvt_pk_bf16_f32 v3, v12, v13
	v_cvt_pk_bf16_f32 v5, v8, v9
	v_lshl_add_u64 v[6:7], v[6:7], 0, v[116:117]
	global_store_dwordx4 v[6:7], v[2:5], off
	s_cbranch_vccz .LBB0_96
	s_nop 0
	v_lshl_add_u32 v2, s42, 8, v145
	v_ashrrev_i32_e32 v3, 31, v2
	v_lshl_add_u64 v[2:3], v[2:3], 2, s[4:5]
	global_load_dword v154, v[2:3], off
	global_load_dword v152, v[2:3], off offset:64
	global_load_dword v150, v[2:3], off offset:128
	global_load_dword v148, v[2:3], off offset:192
	global_load_dword v146, v[2:3], off offset:512
	global_load_dword v144, v[2:3], off offset:576
	global_load_dword v142, v[2:3], off offset:640
	global_load_dword v136, v[2:3], off offset:704
	s_mov_b64 s[60:61], 0
	s_branch .LBB0_96

; #define PG8_STAGE(bufoff, gbase, voff) do { _Pragma("unroll") for (int _i = 0; _i < 2; ++_i) \
;         __builtin_amdgcn_global_load_lds((const unsigned*)((const char*)(gbase) + (voff)[_i]), (LAS unsigned*)(lds + (bufoff) + ldsw + _i * 8192), 16, 0, 0); } while (0)
; #define PG8_LDA(dst, b, h) do { _Pragma("unroll") for (int m = 0; m < 4; ++m) _Pragma("unroll") for (int k = 0; k < 2; ++k) dst[m][k] = *(const LAS bf16x8*)(lds + PG8_SA(b, h) + aoff + m * 2048 + k * 1024); } while (0)
; #define PG8_LDB(dst, b, h) do { _Pragma("unroll") for (int n = 0; n < 2; ++n) _Pragma("unroll") for (int k = 0; k < 2; ++k) dst[n][k] = *(const LAS bf16x8*)(lds + PG8_SB(b, h) + boff + n * 2048 + k * 1024); } while (0)
; #define PG8_MMA(ai, bj, At, Bt) do { __builtin_amdgcn_s_setprio(1); _Pragma("unroll") for (int m = 0; m < 4; ++m) _Pragma("unroll") for (int n = 0; n < 2; ++n) _Pragma("unroll") for (int k = 0; k < 2; ++k) \
;         acc[ai][bj][m][n] = __builtin_amdgcn_mfma_f32_16x16x32_bf16(Bt[n][k], At[m][k], acc[ai][bj][m][n], 0, 0, 0); __builtin_amdgcn_s_setprio(0); } while (0)
; #define PG8_WAIT_V(n) asm volatile("s_waitcnt vmcnt(" #n ")" ::: "memory")
; #define PG8_WAIT_L(n) asm volatile("s_waitcnt lgkmcnt(" #n ")" ::: "memory")
; #define PG8_BAR __builtin_amdgcn_s_barrier()
; #define PG8_SCHED __builtin_amdgcn_sched_barrier(0)
; template <class Epi>
; __device__ __forceinline__ void gemm_phase(LAS unsigned char* lds, const Gemm g, const StaticOrder& S, const Epi& E) {
;     ...
;             const char* a1 = cA + (size_t)(t + 1) * kstep;
;             const char* a2 = last ? nA : cA + (size_t)(t + 2) * kstep; const char* b2 = last ? nB : cB + (size_t)(t + 2) * kstep;
;             const char* a3 = a2 + kstep; const char* b3 = b2 + kstep;
;             PG8_LDB(B0, 0, 0); PG8_SCHED; PG8_LDA(At, 0, 0); PG8_STAGE(PG8_SA(1, 1), a1 + hA, voffA);
;             PG8_WAIT_L(8); PG8_BAR; PG8_WAIT_L(0); PG8_MMA(0, 0, At, B0); PG8_BAR; PG8_SCHED;
;             PG8_LDB(B1, 0, 1); PG8_STAGE(PG8_SB(0, 0), b2, voffB);
;             PG8_BAR; PG8_WAIT_L(0); PG8_MMA(0, 1, At, B1); PG8_BAR;
;             PG8_LDA(At, 0, 1); PG8_STAGE(PG8_SA(0, 0), a2, voffA);
;             PG8_BAR; PG8_WAIT_L(0); PG8_MMA(1, 0, At, B0); PG8_BAR; PG8_SCHED;
;             PG8_STAGE(PG8_SB(0, 1), b2 + hB, voffB);
;             PG8_WAIT_V(6); PG8_BAR; PG8_MMA(1, 1, At, B1); PG8_BAR;
.LBB0_623:
	s_add_u32 s48, s46, 0xfffc0080
	s_addc_u32 s49, s47, -1
	s_add_i32 s67, 0, 0x10000
	v_add_u32_e32 v151, s67, v143
	ds_read_b128 v[156:159], v151
	ds_read_b128 v[160:163], v151 offset:1024
	ds_read_b128 v[164:167], v151 offset:2048
	ds_read_b128 v[168:171], v151 offset:3072
	s_cmp_eq_u32 s66, 12
	s_cselect_b32 s51, s23, s49
	s_cselect_b32 s50, s62, s48
	s_cselect_b32 s49, s15, s65
	s_cselect_b32 s48, s63, s64
	v_lshl_add_u64 v[210:211], s[46:47], 0, v[144:145]
	s_add_i32 m0, s53, 0xc000
	ds_read_b128 v[172:175], v149
	ds_read_b128 v[176:179], v149 offset:1024
	ds_read_b128 v[180:183], v149 offset:2048
	ds_read_b128 v[184:187], v149 offset:3072
	ds_read_b128 v[188:191], v149 offset:4096
	ds_read_b128 v[192:195], v149 offset:5120
	ds_read_b128 v[202:205], v149 offset:6144
	ds_read_b128 v[206:209], v149 offset:7168
	global_load_lds_dwordx4 v[210:211], off
	v_lshl_add_u64 v[210:211], s[46:47], 0, v[146:147]
	s_add_i32 m0, s53, 0xe000
	s_nop 0
	global_load_lds_dwordx4 v[210:211], off
	s_waitcnt lgkmcnt(8)
	s_barrier
	s_waitcnt lgkmcnt(0)
	s_setprio 1
	s_waitcnt lgkmcnt(0)
	v_mfma_f32_16x16x32_bf16 v[126:129], v[156:159], v[172:175], v[126:129]
	v_mfma_f32_16x16x32_bf16 v[122:125], v[164:167], v[172:175], v[122:125]
	v_mfma_f32_16x16x32_bf16 v[118:121], v[156:159], v[180:183], v[118:121]
	v_mfma_f32_16x16x32_bf16 v[110:113], v[164:167], v[180:183], v[110:113]
	v_mfma_f32_16x16x32_bf16 v[102:105], v[156:159], v[188:191], v[102:105]
	v_mfma_f32_16x16x32_bf16 v[94:97], v[164:167], v[188:191], v[94:97]
	v_mfma_f32_16x16x32_bf16 v[86:89], v[156:159], v[202:205], v[86:89]
	v_mfma_f32_16x16x32_bf16 v[78:81], v[164:167], v[202:205], v[78:81]
	v_mfma_f32_16x16x32_bf16 v[126:129], v[160:163], v[176:179], v[126:129]
	v_mfma_f32_16x16x32_bf16 v[122:125], v[168:171], v[176:179], v[122:125]
	v_mfma_f32_16x16x32_bf16 v[118:121], v[160:163], v[184:187], v[118:121]
	v_mfma_f32_16x16x32_bf16 v[110:113], v[168:171], v[184:187], v[110:113]
	v_mfma_f32_16x16x32_bf16 v[102:105], v[160:163], v[192:195], v[102:105]
	v_mfma_f32_16x16x32_bf16 v[94:97], v[168:171], v[192:195], v[94:97]
	v_mfma_f32_16x16x32_bf16 v[86:89], v[160:163], v[206:209], v[86:89]
	v_mfma_f32_16x16x32_bf16 v[78:81], v[168:171], v[206:209], v[78:81]
	s_setprio 0
	s_barrier
	s_add_i32 s70, 0, 0x14000
	s_add_i32 s67, s67, s33
	v_add_u32_e32 v151, s70, v143
	v_lshl_add_u64 v[226:227], s[48:49], 0, v[0:1]
	s_mov_b32 m0, s67
	ds_read_b128 v[210:213], v151
	ds_read_b128 v[214:217], v151 offset:1024
	ds_read_b128 v[218:221], v151 offset:2048
	ds_read_b128 v[222:225], v151 offset:3072
	global_load_lds_dwordx4 v[226:227], off
	v_lshl_add_u64 v[240:241], s[48:49], 0, v[134:135]
	s_add_i32 m0, s67, 0x2000
	s_nop 0
	global_load_lds_dwordx4 v[240:241], off
	s_barrier
	s_waitcnt lgkmcnt(0)
	s_setprio 1
	s_waitcnt lgkmcnt(0)
	v_mfma_f32_16x16x32_bf16 v[114:117], v[210:213], v[172:175], v[114:117]
	v_mfma_f32_16x16x32_bf16 v[106:109], v[218:221], v[172:175], v[106:109]
	v_mfma_f32_16x16x32_bf16 v[98:101], v[210:213], v[180:183], v[98:101]
	v_mfma_f32_16x16x32_bf16 v[90:93], v[218:221], v[180:183], v[90:93]
	v_mfma_f32_16x16x32_bf16 v[82:85], v[210:213], v[188:191], v[82:85]
	v_mfma_f32_16x16x32_bf16 v[74:77], v[218:221], v[188:191], v[74:77]
	v_mfma_f32_16x16x32_bf16 v[70:73], v[210:213], v[202:205], v[70:73]
	v_mfma_f32_16x16x32_bf16 v[66:69], v[218:221], v[202:205], v[66:69]
	v_mfma_f32_16x16x32_bf16 v[114:117], v[214:217], v[176:179], v[114:117]
	v_mfma_f32_16x16x32_bf16 v[106:109], v[222:225], v[176:179], v[106:109]
	v_mfma_f32_16x16x32_bf16 v[98:101], v[214:217], v[184:187], v[98:101]
	v_mfma_f32_16x16x32_bf16 v[90:93], v[222:225], v[184:187], v[90:93]
	v_mfma_f32_16x16x32_bf16 v[82:85], v[214:217], v[192:195], v[82:85]
	v_mfma_f32_16x16x32_bf16 v[74:77], v[222:225], v[192:195], v[74:77]
	v_mfma_f32_16x16x32_bf16 v[70:73], v[214:217], v[206:209], v[70:73]
	v_mfma_f32_16x16x32_bf16 v[66:69], v[222:225], v[206:209], v[66:69]
	s_setprio 0
	s_mov_b32 m0, s53
	v_lshl_add_u64 v[242:243], s[50:51], 0, v[130:131]
	s_barrier
	ds_read_b128 v[172:175], v149 offset:16384
	ds_read_b128 v[176:179], v149 offset:17408
	ds_read_b128 v[180:183], v149 offset:18432
	ds_read_b128 v[184:187], v149 offset:19456
	ds_read_b128 v[188:191], v149 offset:20480
	ds_read_b128 v[192:195], v149 offset:21504
	ds_read_b128 v[202:205], v149 offset:22528
	ds_read_b128 v[206:209], v149 offset:23552
	global_load_lds_dwordx4 v[242:243], off
	v_lshl_add_u64 v[244:245], s[50:51], 0, v[132:133]
	s_mov_b32 m0, s54
	s_nop 0
	global_load_lds_dwordx4 v[244:245], off
	s_barrier
	s_waitcnt lgkmcnt(0)
	s_setprio 1
	s_waitcnt lgkmcnt(0)
	v_mfma_f32_16x16x32_bf16 v[62:65], v[156:159], v[172:175], v[62:65]
	v_mfma_f32_16x16x32_bf16 v[58:61], v[164:167], v[172:175], v[58:61]
	v_mfma_f32_16x16x32_bf16 v[54:57], v[156:159], v[180:183], v[54:57]
	v_mfma_f32_16x16x32_bf16 v[46:49], v[164:167], v[180:183], v[46:49]
	v_mfma_f32_16x16x32_bf16 v[38:41], v[156:159], v[188:191], v[38:41]
	v_mfma_f32_16x16x32_bf16 v[30:33], v[164:167], v[188:191], v[30:33]
	v_mfma_f32_16x16x32_bf16 v[22:25], v[156:159], v[202:205], v[22:25]
	v_mfma_f32_16x16x32_bf16 v[14:17], v[164:167], v[202:205], v[14:17]
	v_mfma_f32_16x16x32_bf16 v[62:65], v[160:163], v[176:179], v[62:65]
	v_mfma_f32_16x16x32_bf16 v[58:61], v[168:171], v[176:179], v[58:61]
	v_mfma_f32_16x16x32_bf16 v[54:57], v[160:163], v[184:187], v[54:57]
	v_mfma_f32_16x16x32_bf16 v[46:49], v[168:171], v[184:187], v[46:49]
	v_mfma_f32_16x16x32_bf16 v[38:41], v[160:163], v[192:195], v[38:41]
	v_mfma_f32_16x16x32_bf16 v[30:33], v[168:171], v[192:195], v[30:33]
	v_mfma_f32_16x16x32_bf16 v[22:25], v[160:163], v[206:209], v[22:25]
	v_mfma_f32_16x16x32_bf16 v[14:17], v[168:171], v[206:209], v[14:17]
	s_setprio 0
	s_barrier
; #define PG8_STAGE(bufoff, gbase, voff) do { _Pragma("unroll") for (int _i = 0; _i < 2; ++_i) \
;         __builtin_amdgcn_global_load_lds((const unsigned*)((const char*)(gbase) + (voff)[_i]), (LAS unsigned*)(lds + (bufoff) + ldsw + _i * 8192), 16, 0, 0); } while (0)
; #define PG8_LDA(dst, b, h) do { _Pragma("unroll") for (int m = 0; m < 4; ++m) _Pragma("unroll") for (int k = 0; k < 2; ++k) dst[m][k] = *(const LAS bf16x8*)(lds + PG8_SA(b, h) + aoff + m * 2048 + k * 1024); } while (0)
; #define PG8_LDB(dst, b, h) do { _Pragma("unroll") for (int n = 0; n < 2; ++n) _Pragma("unroll") for (int k = 0; k < 2; ++k) dst[n][k] = *(const LAS bf16x8*)(lds + PG8_SB(b, h) + boff + n * 2048 + k * 1024); } while (0)
; #define PG8_MMA(ai, bj, At, Bt) do { __builtin_amdgcn_s_setprio(1); _Pragma("unroll") for (int m = 0; m < 4; ++m) _Pragma("unroll") for (int n = 0; n < 2; ++n) _Pragma("unroll") for (int k = 0; k < 2; ++k) \
;         acc[ai][bj][m][n] = __builtin_amdgcn_mfma_f32_16x16x32_bf16(Bt[n][k], At[m][k], acc[ai][bj][m][n], 0, 0, 0); __builtin_amdgcn_s_setprio(0); } while (0)
; #define PG8_WAIT_V(n) asm volatile("s_waitcnt vmcnt(" #n ")" ::: "memory")
; #define PG8_WAIT_L(n) asm volatile("s_waitcnt lgkmcnt(" #n ")" ::: "memory")
; #define PG8_BAR __builtin_amdgcn_s_barrier()
; #define PG8_SCHED __builtin_amdgcn_sched_barrier(0)
; template <class Epi>
; __device__ __forceinline__ void gemm_phase(LAS unsigned char* lds, const Gemm g, const StaticOrder& S, const Epi& E) {
;     ...
;             PG8_STAGE(PG8_SB(0, 1), b2 + hB, voffB);
;             PG8_WAIT_V(6); PG8_BAR; PG8_MMA(1, 1, At, B1); PG8_BAR;
;             PG8_LDB(B0, 1, 0); PG8_SCHED; PG8_LDA(At, 1, 0); PG8_STAGE(PG8_SA(0, 1), a2 + hA, voffA);
;             PG8_WAIT_L(8); PG8_BAR; PG8_WAIT_L(0); PG8_MMA(0, 0, At, B0); PG8_BAR; PG8_SCHED;
;             PG8_LDB(B1, 1, 1); PG8_STAGE(PG8_SB(1, 0), b3, voffB);
;             PG8_BAR; PG8_WAIT_L(0); PG8_MMA(0, 1, At, B1); PG8_BAR;
;             PG8_LDA(At, 1, 1); PG8_STAGE(PG8_SA(1, 0), a3, voffA);
;             PG8_BAR; PG8_WAIT_L(0); PG8_MMA(1, 0, At, B0); PG8_BAR; PG8_SCHED;
	s_add_u32 s68, s48, 0x40000
	s_addc_u32 s69, s49, 0
	s_add_i32 s67, s70, s33
	v_lshl_add_u64 v[156:157], s[68:69], 0, v[0:1]
	s_mov_b32 m0, s67
	s_nop 0
	global_load_lds_dwordx4 v[156:157], off
	v_lshl_add_u64 v[156:157], s[68:69], 0, v[134:135]
	s_add_i32 m0, s67, 0x2000
	s_nop 0
	global_load_lds_dwordx4 v[156:157], off
	s_waitcnt vmcnt(6)
	s_barrier
	s_setprio 1
	v_mfma_f32_16x16x32_bf16 v[50:53], v[210:213], v[172:175], v[50:53]
	v_mfma_f32_16x16x32_bf16 v[42:45], v[218:221], v[172:175], v[42:45]
	v_mfma_f32_16x16x32_bf16 v[34:37], v[210:213], v[180:183], v[34:37]
	v_mfma_f32_16x16x32_bf16 v[26:29], v[218:221], v[180:183], v[26:29]
	v_mfma_f32_16x16x32_bf16 v[18:21], v[210:213], v[188:191], v[18:21]
	v_mfma_f32_16x16x32_bf16 v[10:13], v[218:221], v[188:191], v[10:13]
	v_mfma_f32_16x16x32_bf16 v[6:9], v[210:213], v[202:205], v[6:9]
	v_mfma_f32_16x16x32_bf16 v[2:5], v[218:221], v[202:205], v[2:5]
	v_mfma_f32_16x16x32_bf16 v[50:53], v[214:217], v[176:179], v[50:53]
	v_mfma_f32_16x16x32_bf16 v[42:45], v[222:225], v[176:179], v[42:45]
	v_mfma_f32_16x16x32_bf16 v[34:37], v[214:217], v[184:187], v[34:37]
	v_mfma_f32_16x16x32_bf16 v[26:29], v[222:225], v[184:187], v[26:29]
	v_mfma_f32_16x16x32_bf16 v[18:21], v[214:217], v[192:195], v[18:21]
	v_mfma_f32_16x16x32_bf16 v[10:13], v[222:225], v[192:195], v[10:13]
	v_mfma_f32_16x16x32_bf16 v[6:9], v[214:217], v[206:209], v[6:9]
	v_mfma_f32_16x16x32_bf16 v[2:5], v[222:225], v[206:209], v[2:5]
	s_setprio 0
	s_add_i32 s67, 0, 0x18000
	v_add_u32_e32 v151, s67, v143
	s_barrier
	ds_read_b128 v[156:159], v151
	ds_read_b128 v[160:163], v151 offset:1024
	ds_read_b128 v[164:167], v151 offset:2048
	ds_read_b128 v[168:171], v151 offset:3072
	s_add_u32 s50, s50, 0x40000
	s_addc_u32 s51, s51, 0
	s_mov_b32 m0, s55
	v_lshl_add_u64 v[210:211], s[50:51], 0, v[130:131]
	ds_read_b128 v[172:175], v149 offset:32768
	ds_read_b128 v[176:179], v149 offset:33792
	ds_read_b128 v[180:183], v149 offset:34816
	ds_read_b128 v[184:187], v149 offset:35840
	ds_read_b128 v[188:191], v149 offset:36864
	ds_read_b128 v[192:195], v149 offset:37888
	ds_read_b128 v[202:205], v149 offset:38912
	ds_read_b128 v[206:209], v149 offset:39936
	global_load_lds_dwordx4 v[210:211], off
	v_lshl_add_u64 v[210:211], s[50:51], 0, v[132:133]
	s_mov_b32 m0, s56
	s_nop 0
	global_load_lds_dwordx4 v[210:211], off
	s_waitcnt lgkmcnt(8)
	s_barrier
	s_waitcnt lgkmcnt(0)
	s_setprio 1
	s_waitcnt lgkmcnt(0)
	v_mfma_f32_16x16x32_bf16 v[126:129], v[156:159], v[172:175], v[126:129]
	v_mfma_f32_16x16x32_bf16 v[122:125], v[164:167], v[172:175], v[122:125]
	v_mfma_f32_16x16x32_bf16 v[118:121], v[156:159], v[180:183], v[118:121]
	v_mfma_f32_16x16x32_bf16 v[110:113], v[164:167], v[180:183], v[110:113]
	v_mfma_f32_16x16x32_bf16 v[102:105], v[156:159], v[188:191], v[102:105]
	v_mfma_f32_16x16x32_bf16 v[94:97], v[164:167], v[188:191], v[94:97]
	v_mfma_f32_16x16x32_bf16 v[86:89], v[156:159], v[202:205], v[86:89]
	v_mfma_f32_16x16x32_bf16 v[78:81], v[164:167], v[202:205], v[78:81]
	v_mfma_f32_16x16x32_bf16 v[126:129], v[160:163], v[176:179], v[126:129]
	v_mfma_f32_16x16x32_bf16 v[122:125], v[168:171], v[176:179], v[122:125]
	v_mfma_f32_16x16x32_bf16 v[118:121], v[160:163], v[184:187], v[118:121]
	v_mfma_f32_16x16x32_bf16 v[110:113], v[168:171], v[184:187], v[110:113]
	v_mfma_f32_16x16x32_bf16 v[102:105], v[160:163], v[192:195], v[102:105]
	v_mfma_f32_16x16x32_bf16 v[94:97], v[168:171], v[192:195], v[94:97]
	v_mfma_f32_16x16x32_bf16 v[86:89], v[160:163], v[206:209], v[86:89]
	v_mfma_f32_16x16x32_bf16 v[78:81], v[168:171], v[206:209], v[78:81]
	s_setprio 0
	s_barrier
	s_add_i32 s50, 0, 0x1c000
	s_add_i32 s51, s67, s33
	v_add_u32_e32 v151, s50, v143
	v_lshl_add_u64 v[226:227], v[226:227], 0, s[34:35]
	s_mov_b32 m0, s51
	ds_read_b128 v[210:213], v151
	ds_read_b128 v[214:217], v151 offset:1024
	ds_read_b128 v[218:221], v151 offset:2048
	ds_read_b128 v[222:225], v151 offset:3072
	global_load_lds_dwordx4 v[226:227], off
	v_lshl_add_u64 v[226:227], v[240:241], 0, s[34:35]
	s_add_i32 m0, s51, 0x2000
	s_nop 0
	global_load_lds_dwordx4 v[226:227], off
	s_barrier
	s_waitcnt lgkmcnt(0)
	s_setprio 1
	s_waitcnt lgkmcnt(0)
	v_mfma_f32_16x16x32_bf16 v[114:117], v[210:213], v[172:175], v[114:117]
	v_mfma_f32_16x16x32_bf16 v[106:109], v[218:221], v[172:175], v[106:109]
	v_mfma_f32_16x16x32_bf16 v[98:101], v[210:213], v[180:183], v[98:101]
	v_mfma_f32_16x16x32_bf16 v[90:93], v[218:221], v[180:183], v[90:93]
	v_mfma_f32_16x16x32_bf16 v[82:85], v[210:213], v[188:191], v[82:85]
	v_mfma_f32_16x16x32_bf16 v[74:77], v[218:221], v[188:191], v[74:77]
	v_mfma_f32_16x16x32_bf16 v[70:73], v[210:213], v[202:205], v[70:73]
	v_mfma_f32_16x16x32_bf16 v[66:69], v[218:221], v[202:205], v[66:69]
	v_mfma_f32_16x16x32_bf16 v[114:117], v[214:217], v[176:179], v[114:117]
	v_mfma_f32_16x16x32_bf16 v[106:109], v[222:225], v[176:179], v[106:109]
	v_mfma_f32_16x16x32_bf16 v[98:101], v[214:217], v[184:187], v[98:101]
	v_mfma_f32_16x16x32_bf16 v[90:93], v[222:225], v[184:187], v[90:93]
	v_mfma_f32_16x16x32_bf16 v[82:85], v[214:217], v[192:195], v[82:85]
	v_mfma_f32_16x16x32_bf16 v[74:77], v[222:225], v[192:195], v[74:77]
	v_mfma_f32_16x16x32_bf16 v[70:73], v[214:217], v[206:209], v[70:73]
	v_mfma_f32_16x16x32_bf16 v[66:69], v[222:225], v[206:209], v[66:69]
	s_setprio 0
	s_mov_b32 m0, s58
	v_lshl_add_u64 v[226:227], v[242:243], 0, s[34:35]
	s_barrier
	ds_read_b128 v[172:175], v149 offset:49152
	ds_read_b128 v[176:179], v149 offset:50176
	ds_read_b128 v[180:183], v149 offset:51200
	ds_read_b128 v[184:187], v149 offset:52224
	ds_read_b128 v[188:191], v149 offset:53248
	ds_read_b128 v[192:195], v149 offset:54272
	ds_read_b128 v[202:205], v149 offset:55296
	ds_read_b128 v[206:209], v149 offset:56320
	global_load_lds_dwordx4 v[226:227], off
	v_lshl_add_u64 v[226:227], v[244:245], 0, s[34:35]
	s_mov_b32 m0, s59
	s_nop 0
	global_load_lds_dwordx4 v[226:227], off
	s_barrier
; #define PG8_STAGE(bufoff, gbase, voff) do { _Pragma("unroll") for (int _i = 0; _i < 2; ++_i) \
;         __builtin_amdgcn_global_load_lds((const unsigned*)((const char*)(gbase) + (voff)[_i]), (LAS unsigned*)(lds + (bufoff) + ldsw + _i * 8192), 16, 0, 0); } while (0)
; #define PG8_MMA(ai, bj, At, Bt) do { __builtin_amdgcn_s_setprio(1); _Pragma("unroll") for (int m = 0; m < 4; ++m) _Pragma("unroll") for (int n = 0; n < 2; ++n) _Pragma("unroll") for (int k = 0; k < 2; ++k) \
;         acc[ai][bj][m][n] = __builtin_amdgcn_mfma_f32_16x16x32_bf16(Bt[n][k], At[m][k], acc[ai][bj][m][n], 0, 0, 0); __builtin_amdgcn_s_setprio(0); } while (0)
; #define PG8_WAIT_V(n) asm volatile("s_waitcnt vmcnt(" #n ")" ::: "memory")
; #define PG8_WAIT_L(n) asm volatile("s_waitcnt lgkmcnt(" #n ")" ::: "memory")
; #define PG8_BAR __builtin_amdgcn_s_barrier()
; #define PG8_SCHED __builtin_amdgcn_sched_barrier(0)
; __device__ __forceinline__ u32x4 pack8(const f32x4 a, const f32x4 b) { u32x4 w; w.x = cvt_pk_bf16(a[0], a[1]); w.y = cvt_pk_bf16(a[2], a[3]); w.z = cvt_pk_bf16(b[0], b[1]); w.w = cvt_pk_bf16(b[2], b[3]); return w; }
; template <class Epi>
; __device__ __forceinline__ void gemm_phase(LAS unsigned char* lds, const Gemm g, const StaticOrder& S, const Epi& E) {
;     ...
;             PG8_BAR; PG8_WAIT_L(0); PG8_MMA(1, 0, At, B0); PG8_BAR; PG8_SCHED;
;             PG8_STAGE(PG8_SB(1, 1), b3 + hB, voffB);
;             PG8_WAIT_V(6); PG8_BAR; PG8_MMA(1, 1, At, B1); PG8_BAR;
;         }
;         if constexpr (Epi::HAS_PRE) { E(acc, cur, wr, wc, fr, fq, pre); if (has_next) E.pre(pre, nxt, wr, fr); } else E(acc, cur, wr, wc, fr, fq);
;         if (!has_next) break;
;     __device__ __forceinline__ void operator()(const Acc& acc, const Unit& u, int wr, int wc, int fr, int fq, const RsPre& pr) const {
;         asm volatile("" : "+v"(fr), "+v"(fq));
;         const int row0 = u.pm * 256 + wr * 64 + fr, col0 = u.pn * 256 + wc * 32 + 8 * fq;
;         const float (&rs)[2][4] = pr.rs;
; #pragma unroll
;         for (int ai = 0; ai < 2; ++ai)
; #pragma unroll
;             for (int m = 0; m < 4; ++m) { bf16_t* rowp = O + (size_t)(row0 + ai * 128 + m * 16) * ldc + col0;
; #pragma unroll
;                 for (int bj = 0; bj < 2; ++bj) *(u32x4*)(rowp + bj * 128) = pack8(acc[ai][bj][m][0] * rs[ai][m], acc[ai][bj][m][1] * rs[ai][m]); }
	s_waitcnt lgkmcnt(0)
	s_setprio 1
	s_waitcnt lgkmcnt(0)
	v_mfma_f32_16x16x32_bf16 v[62:65], v[156:159], v[172:175], v[62:65]
	v_mfma_f32_16x16x32_bf16 v[58:61], v[164:167], v[172:175], v[58:61]
	v_mfma_f32_16x16x32_bf16 v[54:57], v[156:159], v[180:183], v[54:57]
	v_mfma_f32_16x16x32_bf16 v[46:49], v[164:167], v[180:183], v[46:49]
	v_mfma_f32_16x16x32_bf16 v[38:41], v[156:159], v[188:191], v[38:41]
	v_mfma_f32_16x16x32_bf16 v[30:33], v[164:167], v[188:191], v[30:33]
	v_mfma_f32_16x16x32_bf16 v[22:25], v[156:159], v[202:205], v[22:25]
	v_mfma_f32_16x16x32_bf16 v[14:17], v[164:167], v[202:205], v[14:17]
	v_mfma_f32_16x16x32_bf16 v[62:65], v[160:163], v[176:179], v[62:65]
	v_mfma_f32_16x16x32_bf16 v[58:61], v[168:171], v[176:179], v[58:61]
	v_mfma_f32_16x16x32_bf16 v[54:57], v[160:163], v[184:187], v[54:57]
	v_mfma_f32_16x16x32_bf16 v[46:49], v[168:171], v[184:187], v[46:49]
	v_mfma_f32_16x16x32_bf16 v[38:41], v[160:163], v[192:195], v[38:41]
	v_mfma_f32_16x16x32_bf16 v[30:33], v[168:171], v[192:195], v[30:33]
	v_mfma_f32_16x16x32_bf16 v[22:25], v[160:163], v[206:209], v[22:25]
	v_mfma_f32_16x16x32_bf16 v[14:17], v[168:171], v[206:209], v[14:17]
	s_setprio 0
	s_barrier
	s_add_u32 s48, s48, 0x40080
	s_addc_u32 s49, s49, 0
	s_add_i32 s50, s50, s33
	v_lshl_add_u64 v[156:157], s[48:49], 0, v[0:1]
	s_mov_b32 m0, s50
	s_nop 0
	global_load_lds_dwordx4 v[156:157], off
	v_lshl_add_u64 v[156:157], s[48:49], 0, v[134:135]
	s_add_i32 m0, s50, 0x2000
	s_nop 0
	global_load_lds_dwordx4 v[156:157], off
	s_waitcnt vmcnt(6)
	s_barrier
	s_setprio 1
	v_mfma_f32_16x16x32_bf16 v[50:53], v[210:213], v[172:175], v[50:53]
	v_mfma_f32_16x16x32_bf16 v[42:45], v[218:221], v[172:175], v[42:45]
	v_mfma_f32_16x16x32_bf16 v[34:37], v[210:213], v[180:183], v[34:37]
	v_mfma_f32_16x16x32_bf16 v[26:29], v[218:221], v[180:183], v[26:29]
	v_mfma_f32_16x16x32_bf16 v[18:21], v[210:213], v[188:191], v[18:21]
	v_mfma_f32_16x16x32_bf16 v[10:13], v[218:221], v[188:191], v[10:13]
	v_mfma_f32_16x16x32_bf16 v[6:9], v[210:213], v[202:205], v[6:9]
	v_mfma_f32_16x16x32_bf16 v[2:5], v[218:221], v[202:205], v[2:5]
	v_mfma_f32_16x16x32_bf16 v[50:53], v[214:217], v[176:179], v[50:53]
	v_mfma_f32_16x16x32_bf16 v[42:45], v[222:225], v[176:179], v[42:45]
	v_mfma_f32_16x16x32_bf16 v[34:37], v[214:217], v[184:187], v[34:37]
	v_mfma_f32_16x16x32_bf16 v[26:29], v[222:225], v[184:187], v[26:29]
	v_mfma_f32_16x16x32_bf16 v[18:21], v[214:217], v[192:195], v[18:21]
	v_mfma_f32_16x16x32_bf16 v[10:13], v[222:225], v[192:195], v[10:13]
	v_mfma_f32_16x16x32_bf16 v[6:9], v[214:217], v[206:209], v[6:9]
	v_mfma_f32_16x16x32_bf16 v[2:5], v[222:225], v[206:209], v[2:5]
	s_setprio 0
	s_add_i32 s66, s66, 2
	s_add_u32 s46, s46, 0x100
	s_addc_u32 s47, s47, 0
	s_add_u32 s64, s64, 0x100
	s_addc_u32 s65, s65, 0
	s_cmp_gt_u32 s66, 13
	s_barrier
	s_cbranch_scc0 .LBB0_623
	v_mov_b32_e32 v151, v137
	v_mov_b32_e32 v153, v139
	s_lshl_b32 s15, s44, 8
	s_add_i32 s15, s15, s52
	v_add_u32_e32 v151, s15, v151
	s_lshl_b32 s15, s45, 8
	s_or_b32 s15, s15, s57
	v_lshl_add_u32 v158, v153, 3, s15
	v_ashrrev_i32_e32 v159, 31, v158
	v_mov_b64_e32 v[156:157], s[20:21]
	v_mad_i64_i32 v[160:161], s[44:45], v151, s96, v[156:157]
	v_lshlrev_b64 v[158:159], 1, v[158:159]
	s_waitcnt vmcnt(6)
	v_pk_mul_f32 v[128:129], v[154:155], v[128:129] op_sel_hi:[0,1]
	v_pk_mul_f32 v[126:127], v[154:155], v[126:127] op_sel_hi:[0,1]
	v_pk_mul_f32 v[162:163], v[154:155], v[124:125] op_sel_hi:[0,1]
	v_pk_mul_f32 v[124:125], v[154:155], v[122:123] op_sel_hi:[0,1]
	v_lshl_add_u64 v[160:161], v[160:161], 0, v[158:159]
	v_cvt_pk_bf16_f32 v122, v126, v127
	v_cvt_pk_bf16_f32 v123, v128, v129
	v_cvt_pk_bf16_f32 v124, v124, v125
	v_cvt_pk_bf16_f32 v125, v162, v163
	global_store_dwordx4 v[160:161], v[122:125], off
	v_pk_mul_f32 v[116:117], v[154:155], v[116:117] op_sel_hi:[0,1]
	v_pk_mul_f32 v[114:115], v[154:155], v[114:115] op_sel_hi:[0,1]
	v_pk_mul_f32 v[122:123], v[154:155], v[108:109] op_sel_hi:[0,1]
	v_pk_mul_f32 v[108:109], v[154:155], v[106:107] op_sel_hi:[0,1]
	v_cvt_pk_bf16_f32 v106, v114, v115
	v_cvt_pk_bf16_f32 v107, v116, v117
	v_cvt_pk_bf16_f32 v108, v108, v109
	v_cvt_pk_bf16_f32 v109, v122, v123
	global_store_dwordx4 v[160:161], v[106:109], off offset:256
	v_pk_mul_f32 v[112:113], v[152:153], v[112:113] op_sel_hi:[0,1]
	v_pk_mul_f32 v[110:111], v[152:153], v[110:111] op_sel_hi:[0,1]
	v_add_u32_e32 v106, 16, v151
	v_mad_i64_i32 v[106:107], s[44:45], v106, s96, v[156:157]
	v_lshl_add_u64 v[114:115], v[106:107], 0, v[158:159]
	v_pk_mul_f32 v[108:109], v[152:153], v[120:121] op_sel_hi:[0,1]
	v_pk_mul_f32 v[106:107], v[152:153], v[118:119] op_sel_hi:[0,1]
	v_cvt_pk_bf16_f32 v106, v106, v107
	v_cvt_pk_bf16_f32 v107, v108, v109
	v_cvt_pk_bf16_f32 v108, v110, v111
	v_cvt_pk_bf16_f32 v109, v112, v113
	global_store_dwordx4 v[114:115], v[106:109], off
	v_pk_mul_f32 v[100:101], v[152:153], v[100:101] op_sel_hi:[0,1]
	v_pk_mul_f32 v[98:99], v[152:153], v[98:99] op_sel_hi:[0,1]
	v_pk_mul_f32 v[106:107], v[152:153], v[92:93] op_sel_hi:[0,1]
	v_pk_mul_f32 v[92:93], v[152:153], v[90:91] op_sel_hi:[0,1]
	v_cvt_pk_bf16_f32 v90, v98, v99
	v_cvt_pk_bf16_f32 v91, v100, v101
	v_cvt_pk_bf16_f32 v92, v92, v93
	v_cvt_pk_bf16_f32 v93, v106, v107
	global_store_dwordx4 v[114:115], v[90:93], off offset:256
	v_pk_mul_f32 v[96:97], v[150:151], v[96:97] op_sel_hi:[0,1]
	v_pk_mul_f32 v[94:95], v[150:151], v[94:95] op_sel_hi:[0,1]
	v_add_u32_e32 v90, 32, v151
	v_mad_i64_i32 v[90:91], s[44:45], v90, s96, v[156:157]
	v_lshl_add_u64 v[98:99], v[90:91], 0, v[158:159]
	v_pk_mul_f32 v[92:93], v[150:151], v[104:105] op_sel_hi:[0,1]
	v_pk_mul_f32 v[90:91], v[150:151], v[102:103] op_sel_hi:[0,1]
; __device__ __forceinline__ u32x4 pack8(const f32x4 a, const f32x4 b) { u32x4 w; w.x = cvt_pk_bf16(a[0], a[1]); w.y = cvt_pk_bf16(a[2], a[3]); w.z = cvt_pk_bf16(b[0], b[1]); w.w = cvt_pk_bf16(b[2], b[3]); return w; }
;     __device__ __forceinline__ void pre(RsPre& r, const Unit& u, int wr, int fr) const {
; #pragma unroll
;         for (int ai = 0; ai < 2; ++ai)
; #pragma unroll
;             for (int m = 0; m < 4; ++m) r.rs[ai][m] = rsv[u.pm * 256 + wr * 64 + fr + ai * 128 + m * 16]; }
;     __device__ __forceinline__ void operator()(const Acc& acc, const Unit& u, int wr, int wc, int fr, int fq, const RsPre& pr) const {
;     ...
; #pragma unroll
;         for (int ai = 0; ai < 2; ++ai)
; #pragma unroll
;             for (int m = 0; m < 4; ++m) { bf16_t* rowp = O + (size_t)(row0 + ai * 128 + m * 16) * ldc + col0;
; #pragma unroll
;                 for (int bj = 0; bj < 2; ++bj) *(u32x4*)(rowp + bj * 128) = pack8(acc[ai][bj][m][0] * rs[ai][m], acc[ai][bj][m][1] * rs[ai][m]); }
	v_cvt_pk_bf16_f32 v90, v90, v91
	v_cvt_pk_bf16_f32 v91, v92, v93
	v_cvt_pk_bf16_f32 v92, v94, v95
	v_cvt_pk_bf16_f32 v93, v96, v97
	global_store_dwordx4 v[98:99], v[90:93], off
	v_pk_mul_f32 v[84:85], v[150:151], v[84:85] op_sel_hi:[0,1]
	v_pk_mul_f32 v[82:83], v[150:151], v[82:83] op_sel_hi:[0,1]
	v_pk_mul_f32 v[90:91], v[150:151], v[76:77] op_sel_hi:[0,1]
	v_pk_mul_f32 v[76:77], v[150:151], v[74:75] op_sel_hi:[0,1]
	v_cvt_pk_bf16_f32 v74, v82, v83
	v_cvt_pk_bf16_f32 v75, v84, v85
	v_cvt_pk_bf16_f32 v76, v76, v77
	v_cvt_pk_bf16_f32 v77, v90, v91
	global_store_dwordx4 v[98:99], v[74:77], off offset:256
	v_pk_mul_f32 v[80:81], v[148:149], v[80:81] op_sel_hi:[0,1]
	v_pk_mul_f32 v[78:79], v[148:149], v[78:79] op_sel_hi:[0,1]
	v_add_u32_e32 v74, 48, v151
	v_mad_i64_i32 v[74:75], s[44:45], v74, s96, v[156:157]
	v_lshl_add_u64 v[82:83], v[74:75], 0, v[158:159]
	v_pk_mul_f32 v[76:77], v[148:149], v[88:89] op_sel_hi:[0,1]
	v_pk_mul_f32 v[74:75], v[148:149], v[86:87] op_sel_hi:[0,1]
	v_cvt_pk_bf16_f32 v74, v74, v75
	v_cvt_pk_bf16_f32 v75, v76, v77
	v_cvt_pk_bf16_f32 v76, v78, v79
	v_cvt_pk_bf16_f32 v77, v80, v81
	global_store_dwordx4 v[82:83], v[74:77], off
	v_pk_mul_f32 v[72:73], v[148:149], v[72:73] op_sel_hi:[0,1]
	v_pk_mul_f32 v[70:71], v[148:149], v[70:71] op_sel_hi:[0,1]
	v_pk_mul_f32 v[74:75], v[148:149], v[68:69] op_sel_hi:[0,1]
	v_pk_mul_f32 v[68:69], v[148:149], v[66:67] op_sel_hi:[0,1]
	v_cvt_pk_bf16_f32 v66, v70, v71
	v_cvt_pk_bf16_f32 v67, v72, v73
	v_cvt_pk_bf16_f32 v68, v68, v69
	v_cvt_pk_bf16_f32 v69, v74, v75
	global_store_dwordx4 v[82:83], v[66:69], off offset:256
	v_pk_mul_f32 v[64:65], v[142:143], v[64:65] op_sel_hi:[0,1]
	v_pk_mul_f32 v[62:63], v[142:143], v[62:63] op_sel_hi:[0,1]
	v_add_u32_e32 v66, 0x80, v151
	v_mad_i64_i32 v[66:67], s[44:45], v66, s96, v[156:157]
	v_pk_mul_f32 v[68:69], v[142:143], v[60:61] op_sel_hi:[0,1]
	v_pk_mul_f32 v[60:61], v[142:143], v[58:59] op_sel_hi:[0,1]
	v_lshl_add_u64 v[66:67], v[66:67], 0, v[158:159]
	v_cvt_pk_bf16_f32 v58, v62, v63
	v_cvt_pk_bf16_f32 v59, v64, v65
	v_cvt_pk_bf16_f32 v60, v60, v61
	v_cvt_pk_bf16_f32 v61, v68, v69
	global_store_dwordx4 v[66:67], v[58:61], off
	v_pk_mul_f32 v[52:53], v[142:143], v[52:53] op_sel_hi:[0,1]
	v_pk_mul_f32 v[50:51], v[142:143], v[50:51] op_sel_hi:[0,1]
	v_pk_mul_f32 v[58:59], v[142:143], v[44:45] op_sel_hi:[0,1]
	v_pk_mul_f32 v[44:45], v[142:143], v[42:43] op_sel_hi:[0,1]
	v_cvt_pk_bf16_f32 v42, v50, v51
	v_cvt_pk_bf16_f32 v43, v52, v53
	v_cvt_pk_bf16_f32 v44, v44, v45
	v_cvt_pk_bf16_f32 v45, v58, v59
	global_store_dwordx4 v[66:67], v[42:45], off offset:256
	v_pk_mul_f32 v[48:49], v[140:141], v[48:49] op_sel_hi:[0,1]
	v_pk_mul_f32 v[46:47], v[140:141], v[46:47] op_sel_hi:[0,1]
	v_add_u32_e32 v42, 0x90, v151
	v_mad_i64_i32 v[42:43], s[44:45], v42, s96, v[156:157]
	v_lshl_add_u64 v[50:51], v[42:43], 0, v[158:159]
	v_pk_mul_f32 v[44:45], v[140:141], v[56:57] op_sel_hi:[0,1]
	v_pk_mul_f32 v[42:43], v[140:141], v[54:55] op_sel_hi:[0,1]
	v_cvt_pk_bf16_f32 v42, v42, v43
	v_cvt_pk_bf16_f32 v43, v44, v45
	v_cvt_pk_bf16_f32 v44, v46, v47
	v_cvt_pk_bf16_f32 v45, v48, v49
	global_store_dwordx4 v[50:51], v[42:45], off
	v_pk_mul_f32 v[36:37], v[140:141], v[36:37] op_sel_hi:[0,1]
	v_pk_mul_f32 v[34:35], v[140:141], v[34:35] op_sel_hi:[0,1]
	v_pk_mul_f32 v[42:43], v[140:141], v[28:29] op_sel_hi:[0,1]
	v_pk_mul_f32 v[28:29], v[140:141], v[26:27] op_sel_hi:[0,1]
	v_cvt_pk_bf16_f32 v26, v34, v35
	v_cvt_pk_bf16_f32 v27, v36, v37
	v_cvt_pk_bf16_f32 v28, v28, v29
	v_cvt_pk_bf16_f32 v29, v42, v43
	global_store_dwordx4 v[50:51], v[26:29], off offset:256
	v_pk_mul_f32 v[32:33], v[138:139], v[32:33] op_sel_hi:[0,1]
	v_pk_mul_f32 v[30:31], v[138:139], v[30:31] op_sel_hi:[0,1]
	v_add_u32_e32 v26, 0xa0, v151
	v_mad_i64_i32 v[26:27], s[44:45], v26, s96, v[156:157]
	v_lshl_add_u64 v[34:35], v[26:27], 0, v[158:159]
	v_pk_mul_f32 v[28:29], v[138:139], v[40:41] op_sel_hi:[0,1]
	v_pk_mul_f32 v[26:27], v[138:139], v[38:39] op_sel_hi:[0,1]
	v_cvt_pk_bf16_f32 v26, v26, v27
	v_cvt_pk_bf16_f32 v27, v28, v29
	v_cvt_pk_bf16_f32 v28, v30, v31
	v_cvt_pk_bf16_f32 v29, v32, v33
	global_store_dwordx4 v[34:35], v[26:29], off
	v_pk_mul_f32 v[20:21], v[138:139], v[20:21] op_sel_hi:[0,1]
	v_pk_mul_f32 v[18:19], v[138:139], v[18:19] op_sel_hi:[0,1]
	v_pk_mul_f32 v[26:27], v[138:139], v[12:13] op_sel_hi:[0,1]
	v_pk_mul_f32 v[12:13], v[138:139], v[10:11] op_sel_hi:[0,1]
	v_cvt_pk_bf16_f32 v10, v18, v19
	v_cvt_pk_bf16_f32 v11, v20, v21
	v_cvt_pk_bf16_f32 v12, v12, v13
	v_cvt_pk_bf16_f32 v13, v26, v27
	global_store_dwordx4 v[34:35], v[10:13], off offset:256
	v_pk_mul_f32 v[16:17], v[136:137], v[16:17] op_sel_hi:[0,1]
	v_pk_mul_f32 v[14:15], v[136:137], v[14:15] op_sel_hi:[0,1]
	v_add_u32_e32 v10, 0xb0, v151
	v_mad_i64_i32 v[10:11], s[44:45], v10, s96, v[156:157]
	v_lshl_add_u64 v[18:19], v[10:11], 0, v[158:159]
	v_pk_mul_f32 v[12:13], v[136:137], v[24:25] op_sel_hi:[0,1]
	v_pk_mul_f32 v[10:11], v[136:137], v[22:23] op_sel_hi:[0,1]
	v_cvt_pk_bf16_f32 v10, v10, v11
	v_cvt_pk_bf16_f32 v11, v12, v13
	v_cvt_pk_bf16_f32 v12, v14, v15
	v_cvt_pk_bf16_f32 v13, v16, v17
	global_store_dwordx4 v[18:19], v[10:13], off
	v_pk_mul_f32 v[8:9], v[136:137], v[8:9] op_sel_hi:[0,1]
	v_pk_mul_f32 v[6:7], v[136:137], v[6:7] op_sel_hi:[0,1]
	v_pk_mul_f32 v[10:11], v[136:137], v[4:5] op_sel_hi:[0,1]
	v_pk_mul_f32 v[4:5], v[136:137], v[2:3] op_sel_hi:[0,1]
	v_cvt_pk_bf16_f32 v2, v6, v7
	v_cvt_pk_bf16_f32 v3, v8, v9
	v_cvt_pk_bf16_f32 v4, v4, v5
	v_cvt_pk_bf16_f32 v5, v10, v11
	s_mov_b64 s[44:45], -1
	s_and_b64 vcc, vcc, exec
	global_store_dwordx4 v[18:19], v[2:5], off offset:256
	s_cbranch_vccz .LBB0_615
	s_nop 0
	v_lshl_add_u32 v2, s22, 8, v141
	v_ashrrev_i32_e32 v3, 31, v2
	v_lshl_add_u64 v[2:3], v[2:3], 2, s[10:11]
	global_load_dword v154, v[2:3], off
	global_load_dword v152, v[2:3], off offset:64
	global_load_dword v150, v[2:3], off offset:128
	global_load_dword v148, v[2:3], off offset:192
	global_load_dword v142, v[2:3], off offset:512
	global_load_dword v140, v[2:3], off offset:576
	global_load_dword v138, v[2:3], off offset:640
	global_load_dword v136, v[2:3], off offset:704
	s_mov_b64 s[44:45], 0
	s_branch .LBB0_615
